# K-loops: 4 of the 6 LDS-DMA pieces of each SP2 load segment issued inside the following MFMA segment (vmcnt 8,4,8,4), m0 write wait-state order fixed
# baseline (speedup 1.0000x reference)
; #define PG8_STAGE(bufoff, gbase, voff) do { _Pragma("unroll") for (int _i = 0; _i < 2; ++_i) \
;         __builtin_amdgcn_global_load_lds((const unsigned*)((const char*)(gbase) + (voff)[_i]), (PG8_LAS unsigned*)(lds + (bufoff) + ldsw + _i * 8192), 16, 0, 0); } while (0)
; #define PG8_LDA(dst, b, h) do { _Pragma("unroll") for (int m = 0; m < 4; ++m) _Pragma("unroll") for (int k = 0; k < 2; ++k) dst[m][k] = *(const PG8_LAS bf16x8*)(lds + PG8_SA(b, h) + aoff + m * 2048 + k * 1024); } while (0)
; #define PG8_LDB(dst, b, h) do { _Pragma("unroll") for (int n = 0; n < 2; ++n) _Pragma("unroll") for (int k = 0; k < 2; ++k) dst[n][k] = *(const PG8_LAS bf16x8*)(lds + PG8_SB(b, h) + boff + n * 2048 + k * 1024); } while (0)
; #define PG8_MMA(ai, bj, At, Bt) do { __builtin_amdgcn_s_setprio(1); _Pragma("unroll") for (int m = 0; m < 4; ++m) _Pragma("unroll") for (int n = 0; n < 2; ++n) _Pragma("unroll") for (int k = 0; k < 2; ++k) \
;         acc[ai][bj][m][n] = __builtin_amdgcn_mfma_f32_16x16x32_bf16(Bt[n][k], At[m][k], acc[ai][bj][m][n], 0, 0, 0); __builtin_amdgcn_s_setprio(0); } while (0)
; #define PG8_WAIT_V(n) asm volatile("s_waitcnt vmcnt(" #n ")" ::: "memory")
; #define PG8_WAIT_L(n) asm volatile("s_waitcnt lgkmcnt(" #n ")" ::: "memory")
; #define PG8_BAR __builtin_amdgcn_s_barrier()
; #define PG8_SCHED __builtin_amdgcn_sched_barrier(0)
; template <class Epi, class Sched, bool ALIGN_EPI = false, bool SP2 = false>
; __device__ __forceinline__ void gemm_phase(PG8_LAS unsigned char* lds, const Gemm g, const Sched& S, const Epi& E) {
;     ...
;             const bool last = (t == nt - 2);
;             const char* a1 = cA + (size_t)(t + 1) * kstep;
;             const char* a2 = last ? nA : cA + (size_t)(t + 2) * kstep; const char* b2 = last ? nB : cB + (size_t)(t + 2) * kstep;
;             const char* a3 = a2 + kstep; const char* b3 = b2 + kstep;
;             if (last && has_next) S.a_ready(nxt);
;             if constexpr (SP2) {
;             PG8_LDB(B0, 0, 0); PG8_LDB(B1, 0, 1); PG8_SCHED; PG8_LDA(At, 0, 0); PG8_STAGE(PG8_SA(1, 1), a1 + hstepA, voffA);
;             PG8_WAIT_V(8); PG8_WAIT_L(0); PG8_BAR; PG8_MMA(0, 0, At, B0); PG8_MMA(0, 1, At, B1); PG8_BAR; PG8_SCHED;
;             PG8_LDA(At, 0, 1); PG8_STAGE(PG8_SB(0, 0), b2, voffB); PG8_STAGE(PG8_SB(0, 1), b2 + hstepB, voffB); PG8_STAGE(PG8_SA(0, 0), a2, voffA);
.LBB0_171:
	v_add_u32_e32 v76, 0x10000, v162
	v_add_u32_e32 v158, 0x14000, v162
	ds_read_b128 v[64:67], v76
	ds_read_b128 v[68:71], v76 offset:1024
	ds_read_b128 v[72:75], v76 offset:2048
	ds_read_b128 v[76:79], v76 offset:3072
	ds_read_b128 v[154:157], v158
	ds_read_b128 v[164:167], v158 offset:1024
	ds_read_b128 v[168:171], v158 offset:2048
	ds_read_b128 v[172:175], v158 offset:3072
	ds_read_b128 v[176:179], v163
	ds_read_b128 v[180:183], v163 offset:1024
	ds_read_b128 v[184:187], v163 offset:2048
	ds_read_b128 v[194:197], v163 offset:3072
	ds_read_b128 v[230:233], v163 offset:4096
	ds_read_b128 v[234:237], v163 offset:5120
	ds_read_b128 v[238:241], v163 offset:6144
	ds_read_b128 v[242:245], v163 offset:7168
	s_add_u32 s50, s8, 0xfffc0080
	s_addc_u32 s51, s9, -1
	s_add_i32 s60, 0, 0x10000
	s_cmp_eq_u32 s59, 12
	s_cselect_b32 s53, s11, s51
	s_cselect_b32 s52, s37, s50
	s_cselect_b32 s51, s35, s58
	s_cselect_b32 s50, s54, s55
	s_add_i32 s62, 0, 0x14000
	s_add_i32 m0, s57, 0xc000
	v_lshl_add_u64 v[158:159], s[8:9], 0, v[150:151]
	global_load_lds_dwordx4 v[158:159], off
	s_add_i32 m0, s57, 0xe000
	v_lshl_add_u64 v[158:159], s[8:9], 0, v[152:153]
	global_load_lds_dwordx4 v[158:159], off
	s_waitcnt vmcnt(8)
	s_waitcnt lgkmcnt(0)
	s_barrier
	s_setprio 1
	s_waitcnt lgkmcnt(0)
	v_mfma_f32_16x16x32_bf16 v[140:143], v[64:67], v[176:179], v[140:143]
	v_mfma_f32_16x16x32_bf16 v[136:139], v[72:75], v[176:179], v[136:139]
	v_mfma_f32_16x16x32_bf16 v[124:127], v[64:67], v[184:187], v[124:127]
	v_mfma_f32_16x16x32_bf16 v[120:123], v[72:75], v[184:187], v[120:123]
	v_mfma_f32_16x16x32_bf16 v[108:111], v[64:67], v[230:233], v[108:111]
	v_mfma_f32_16x16x32_bf16 v[104:107], v[72:75], v[230:233], v[104:107]
	v_mfma_f32_16x16x32_bf16 v[92:95], v[64:67], v[238:241], v[92:95]
	v_mfma_f32_16x16x32_bf16 v[88:91], v[72:75], v[238:241], v[88:91]
	v_mfma_f32_16x16x32_bf16 v[140:143], v[68:71], v[180:183], v[140:143]
	v_mfma_f32_16x16x32_bf16 v[136:139], v[76:79], v[180:183], v[136:139]
	v_mfma_f32_16x16x32_bf16 v[124:127], v[68:71], v[194:197], v[124:127]
	v_mfma_f32_16x16x32_bf16 v[120:123], v[76:79], v[194:197], v[120:123]
	v_mfma_f32_16x16x32_bf16 v[108:111], v[68:71], v[234:237], v[108:111]
	v_mfma_f32_16x16x32_bf16 v[104:107], v[76:79], v[234:237], v[104:107]
	v_mfma_f32_16x16x32_bf16 v[92:95], v[68:71], v[242:245], v[92:95]
	v_mfma_f32_16x16x32_bf16 v[88:91], v[76:79], v[242:245], v[88:91]
	s_setprio 0
	s_setprio 1
	v_mfma_f32_16x16x32_bf16 v[132:135], v[154:157], v[176:179], v[132:135]
	v_mfma_f32_16x16x32_bf16 v[128:131], v[168:171], v[176:179], v[128:131]
	v_mfma_f32_16x16x32_bf16 v[116:119], v[154:157], v[184:187], v[116:119]
	v_mfma_f32_16x16x32_bf16 v[112:115], v[168:171], v[184:187], v[112:115]
	v_mfma_f32_16x16x32_bf16 v[100:103], v[154:157], v[230:233], v[100:103]
	v_mfma_f32_16x16x32_bf16 v[96:99], v[168:171], v[230:233], v[96:99]
	v_mfma_f32_16x16x32_bf16 v[84:87], v[154:157], v[238:241], v[84:87]
	v_mfma_f32_16x16x32_bf16 v[80:83], v[168:171], v[238:241], v[80:83]
	v_mfma_f32_16x16x32_bf16 v[132:135], v[164:167], v[180:183], v[132:135]
	v_mfma_f32_16x16x32_bf16 v[128:131], v[172:175], v[180:183], v[128:131]
	v_mfma_f32_16x16x32_bf16 v[116:119], v[164:167], v[194:197], v[116:119]
	v_mfma_f32_16x16x32_bf16 v[112:115], v[172:175], v[194:197], v[112:115]
	v_mfma_f32_16x16x32_bf16 v[100:103], v[164:167], v[234:237], v[100:103]
	v_mfma_f32_16x16x32_bf16 v[96:99], v[172:175], v[234:237], v[96:99]
	v_mfma_f32_16x16x32_bf16 v[84:87], v[164:167], v[242:245], v[84:87]
	v_mfma_f32_16x16x32_bf16 v[80:83], v[172:175], v[242:245], v[80:83]
	s_setprio 0
	s_barrier
	ds_read_b128 v[176:179], v163 offset:16384
	ds_read_b128 v[180:183], v163 offset:17408
	ds_read_b128 v[184:187], v163 offset:18432
	ds_read_b128 v[194:197], v163 offset:19456
	ds_read_b128 v[230:233], v163 offset:20480
	ds_read_b128 v[234:237], v163 offset:21504
	ds_read_b128 v[238:241], v163 offset:22528
	ds_read_b128 v[242:245], v163 offset:23552
	s_add_i32 s60, s60, s69
	s_mov_b32 m0, s60
	v_lshl_add_u64 v[158:159], s[50:51], 0, v[188:189]
	global_load_lds_dwordx4 v[158:159], off
	s_add_i32 m0, s60, 0x2000
	s_add_u32 s60, s50, 0x40000
	v_lshl_add_u64 v[246:247], s[50:51], 0, v[148:149]
	s_addc_u32 s61, s51, 0
	s_add_i32 s62, s62, s69
	global_load_lds_dwordx4 v[246:247], off
	s_waitcnt vmcnt(4)
	s_waitcnt lgkmcnt(0)
	s_barrier
; #define PG8_STAGE(bufoff, gbase, voff) do { _Pragma("unroll") for (int _i = 0; _i < 2; ++_i) \
;         __builtin_amdgcn_global_load_lds((const unsigned*)((const char*)(gbase) + (voff)[_i]), (PG8_LAS unsigned*)(lds + (bufoff) + ldsw + _i * 8192), 16, 0, 0); } while (0)
; #define PG8_LDA(dst, b, h) do { _Pragma("unroll") for (int m = 0; m < 4; ++m) _Pragma("unroll") for (int k = 0; k < 2; ++k) dst[m][k] = *(const PG8_LAS bf16x8*)(lds + PG8_SA(b, h) + aoff + m * 2048 + k * 1024); } while (0)
; #define PG8_LDB(dst, b, h) do { _Pragma("unroll") for (int n = 0; n < 2; ++n) _Pragma("unroll") for (int k = 0; k < 2; ++k) dst[n][k] = *(const PG8_LAS bf16x8*)(lds + PG8_SB(b, h) + boff + n * 2048 + k * 1024); } while (0)
; #define PG8_MMA(ai, bj, At, Bt) do { __builtin_amdgcn_s_setprio(1); _Pragma("unroll") for (int m = 0; m < 4; ++m) _Pragma("unroll") for (int n = 0; n < 2; ++n) _Pragma("unroll") for (int k = 0; k < 2; ++k) \
;         acc[ai][bj][m][n] = __builtin_amdgcn_mfma_f32_16x16x32_bf16(Bt[n][k], At[m][k], acc[ai][bj][m][n], 0, 0, 0); __builtin_amdgcn_s_setprio(0); } while (0)
; #define PG8_WAIT_V(n) asm volatile("s_waitcnt vmcnt(" #n ")" ::: "memory")
; #define PG8_WAIT_L(n) asm volatile("s_waitcnt lgkmcnt(" #n ")" ::: "memory")
; #define PG8_BAR __builtin_amdgcn_s_barrier()
; #define PG8_SCHED __builtin_amdgcn_sched_barrier(0)
; template <class Epi, class Sched, bool ALIGN_EPI = false, bool SP2 = false>
; __device__ __forceinline__ void gemm_phase(PG8_LAS unsigned char* lds, const Gemm g, const Sched& S, const Epi& E) {
;     ...
;             PG8_WAIT_V(8); PG8_WAIT_L(0); PG8_BAR; PG8_MMA(1, 0, At, B0); PG8_MMA(1, 1, At, B1); PG8_BAR; PG8_SCHED;
;             PG8_LDB(B0, 1, 0); PG8_LDB(B1, 1, 1); PG8_SCHED; PG8_LDA(At, 1, 0); PG8_STAGE(PG8_SA(0, 1), a2 + hstepA, voffA);
;             PG8_WAIT_V(8); PG8_WAIT_L(0); PG8_BAR; PG8_MMA(0, 0, At, B0); PG8_MMA(0, 1, At, B1); PG8_BAR; PG8_SCHED;
	s_setprio 1
	s_waitcnt lgkmcnt(0)
	v_mfma_f32_16x16x32_bf16 v[60:63], v[64:67], v[176:179], v[60:63]
	v_mfma_f32_16x16x32_bf16 v[56:59], v[72:75], v[176:179], v[56:59]
	v_lshl_add_u64 v[248:249], s[60:61], 0, v[188:189]
	s_mov_b32 m0, s62
	v_lshl_add_u64 v[250:251], s[52:53], 0, v[146:147]
	global_load_lds_dwordx4 v[248:249], off
	v_mfma_f32_16x16x32_bf16 v[44:47], v[64:67], v[184:187], v[44:47]
	v_mfma_f32_16x16x32_bf16 v[40:43], v[72:75], v[184:187], v[40:43]
	v_mfma_f32_16x16x32_bf16 v[28:31], v[64:67], v[230:233], v[28:31]
	v_mfma_f32_16x16x32_bf16 v[24:27], v[72:75], v[230:233], v[24:27]
	v_mfma_f32_16x16x32_bf16 v[12:15], v[64:67], v[238:241], v[12:15]
	v_mfma_f32_16x16x32_bf16 v[8:11], v[72:75], v[238:241], v[8:11]
	v_mfma_f32_16x16x32_bf16 v[60:63], v[68:71], v[180:183], v[60:63]
	v_mfma_f32_16x16x32_bf16 v[56:59], v[76:79], v[180:183], v[56:59]
	s_add_i32 m0, s62, 0x2000
	v_lshl_add_u64 v[248:249], s[60:61], 0, v[148:149]
	global_load_lds_dwordx4 v[248:249], off
	v_mfma_f32_16x16x32_bf16 v[44:47], v[68:71], v[194:197], v[44:47]
	v_mfma_f32_16x16x32_bf16 v[40:43], v[76:79], v[194:197], v[40:43]
	v_mfma_f32_16x16x32_bf16 v[28:31], v[68:71], v[234:237], v[28:31]
	v_mfma_f32_16x16x32_bf16 v[24:27], v[76:79], v[234:237], v[24:27]
	v_mfma_f32_16x16x32_bf16 v[12:15], v[68:71], v[242:245], v[12:15]
	v_mfma_f32_16x16x32_bf16 v[8:11], v[76:79], v[242:245], v[8:11]
	s_setprio 0
	s_setprio 1
	v_mfma_f32_16x16x32_bf16 v[52:55], v[154:157], v[176:179], v[52:55]
	v_mfma_f32_16x16x32_bf16 v[48:51], v[168:171], v[176:179], v[48:51]
	s_mov_b32 m0, s57
	v_lshl_add_u64 v[248:249], s[52:53], 0, v[144:145]
	global_load_lds_dwordx4 v[248:249], off
	v_mfma_f32_16x16x32_bf16 v[36:39], v[154:157], v[184:187], v[36:39]
	v_mfma_f32_16x16x32_bf16 v[32:35], v[168:171], v[184:187], v[32:35]
	v_mfma_f32_16x16x32_bf16 v[20:23], v[154:157], v[230:233], v[20:23]
	v_mfma_f32_16x16x32_bf16 v[16:19], v[168:171], v[230:233], v[16:19]
	v_mfma_f32_16x16x32_bf16 v[4:7], v[154:157], v[238:241], v[4:7]
	v_mfma_f32_16x16x32_bf16 v[0:3], v[168:171], v[238:241], v[0:3]
	v_mfma_f32_16x16x32_bf16 v[52:55], v[164:167], v[180:183], v[52:55]
	v_mfma_f32_16x16x32_bf16 v[48:51], v[172:175], v[180:183], v[48:51]
	s_mov_b32 m0, s78
	s_nop 0
	global_load_lds_dwordx4 v[250:251], off
	v_mfma_f32_16x16x32_bf16 v[36:39], v[164:167], v[194:197], v[36:39]
	v_mfma_f32_16x16x32_bf16 v[32:35], v[172:175], v[194:197], v[32:35]
	v_mfma_f32_16x16x32_bf16 v[20:23], v[164:167], v[234:237], v[20:23]
	v_mfma_f32_16x16x32_bf16 v[16:19], v[172:175], v[234:237], v[16:19]
	v_mfma_f32_16x16x32_bf16 v[4:7], v[164:167], v[242:245], v[4:7]
	v_mfma_f32_16x16x32_bf16 v[0:3], v[172:175], v[242:245], v[0:3]
	s_setprio 0
	s_barrier
	v_add_u32_e32 v76, 0x18000, v162
	v_add_u32_e32 v172, 0x1c000, v162
	ds_read_b128 v[64:67], v76
	ds_read_b128 v[68:71], v76 offset:1024
	ds_read_b128 v[72:75], v76 offset:2048
	ds_read_b128 v[76:79], v76 offset:3072
	ds_read_b128 v[154:157], v172
	ds_read_b128 v[164:167], v172 offset:1024
	ds_read_b128 v[168:171], v172 offset:2048
	ds_read_b128 v[172:175], v172 offset:3072
	ds_read_b128 v[176:179], v163 offset:32768
	ds_read_b128 v[180:183], v163 offset:33792
	ds_read_b128 v[184:187], v163 offset:34816
	ds_read_b128 v[194:197], v163 offset:35840
	ds_read_b128 v[230:233], v163 offset:36864
	ds_read_b128 v[234:237], v163 offset:37888
	ds_read_b128 v[238:241], v163 offset:38912
	ds_read_b128 v[242:245], v163 offset:39936
	s_add_i32 s60, 0, 0x18000
	s_add_i32 s61, 0, 0x1c000
	s_add_u32 s52, s52, 0x40000
	s_addc_u32 s53, s53, 0
	s_mov_b32 m0, s81
	v_lshl_add_u64 v[252:253], s[52:53], 0, v[144:145]
	global_load_lds_dwordx4 v[252:253], off
	s_mov_b32 m0, s80
	v_lshl_add_u64 v[252:253], s[52:53], 0, v[146:147]
	global_load_lds_dwordx4 v[252:253], off
	s_waitcnt vmcnt(8)
	s_waitcnt lgkmcnt(0)
	s_barrier
; #define PG8_STAGE(bufoff, gbase, voff) do { _Pragma("unroll") for (int _i = 0; _i < 2; ++_i) \
;         __builtin_amdgcn_global_load_lds((const unsigned*)((const char*)(gbase) + (voff)[_i]), (PG8_LAS unsigned*)(lds + (bufoff) + ldsw + _i * 8192), 16, 0, 0); } while (0)
; #define PG8_LDA(dst, b, h) do { _Pragma("unroll") for (int m = 0; m < 4; ++m) _Pragma("unroll") for (int k = 0; k < 2; ++k) dst[m][k] = *(const PG8_LAS bf16x8*)(lds + PG8_SA(b, h) + aoff + m * 2048 + k * 1024); } while (0)
; #define PG8_MMA(ai, bj, At, Bt) do { __builtin_amdgcn_s_setprio(1); _Pragma("unroll") for (int m = 0; m < 4; ++m) _Pragma("unroll") for (int n = 0; n < 2; ++n) _Pragma("unroll") for (int k = 0; k < 2; ++k) \
;         acc[ai][bj][m][n] = __builtin_amdgcn_mfma_f32_16x16x32_bf16(Bt[n][k], At[m][k], acc[ai][bj][m][n], 0, 0, 0); __builtin_amdgcn_s_setprio(0); } while (0)
; #define PG8_WAIT_V(n) asm volatile("s_waitcnt vmcnt(" #n ")" ::: "memory")
; #define PG8_WAIT_L(n) asm volatile("s_waitcnt lgkmcnt(" #n ")" ::: "memory")
; #define PG8_BAR __builtin_amdgcn_s_barrier()
; #define PG8_SCHED __builtin_amdgcn_sched_barrier(0)
; template <class Epi, class Sched, bool ALIGN_EPI = false, bool SP2 = false>
; __device__ __forceinline__ void gemm_phase(PG8_LAS unsigned char* lds, const Gemm g, const Sched& S, const Epi& E) {
;     ...
;         for (int t = 0; t < nt; t += 2) {
;     ...
;             PG8_WAIT_V(8); PG8_WAIT_L(0); PG8_BAR; PG8_MMA(0, 0, At, B0); PG8_MMA(0, 1, At, B1); PG8_BAR; PG8_SCHED;
;             PG8_LDA(At, 1, 1); PG8_STAGE(PG8_SB(1, 0), b3, voffB); PG8_STAGE(PG8_SB(1, 1), b3 + hstepB, voffB); PG8_STAGE(PG8_SA(1, 0), a3, voffA);
;             PG8_WAIT_V(8); PG8_WAIT_L(0); PG8_BAR; PG8_MMA(1, 0, At, B0); PG8_MMA(1, 1, At, B1); PG8_BAR; PG8_SCHED;
	s_setprio 1
	s_waitcnt lgkmcnt(0)
	v_mfma_f32_16x16x32_bf16 v[140:143], v[64:67], v[176:179], v[140:143]
	v_mfma_f32_16x16x32_bf16 v[136:139], v[72:75], v[176:179], v[136:139]
	v_mfma_f32_16x16x32_bf16 v[124:127], v[64:67], v[184:187], v[124:127]
	v_mfma_f32_16x16x32_bf16 v[120:123], v[72:75], v[184:187], v[120:123]
	v_mfma_f32_16x16x32_bf16 v[108:111], v[64:67], v[230:233], v[108:111]
	v_mfma_f32_16x16x32_bf16 v[104:107], v[72:75], v[230:233], v[104:107]
	v_mfma_f32_16x16x32_bf16 v[92:95], v[64:67], v[238:241], v[92:95]
	v_mfma_f32_16x16x32_bf16 v[88:91], v[72:75], v[238:241], v[88:91]
	v_mfma_f32_16x16x32_bf16 v[140:143], v[68:71], v[180:183], v[140:143]
	v_mfma_f32_16x16x32_bf16 v[136:139], v[76:79], v[180:183], v[136:139]
	v_mfma_f32_16x16x32_bf16 v[124:127], v[68:71], v[194:197], v[124:127]
	v_mfma_f32_16x16x32_bf16 v[120:123], v[76:79], v[194:197], v[120:123]
	v_mfma_f32_16x16x32_bf16 v[108:111], v[68:71], v[234:237], v[108:111]
	v_mfma_f32_16x16x32_bf16 v[104:107], v[76:79], v[234:237], v[104:107]
	v_mfma_f32_16x16x32_bf16 v[92:95], v[68:71], v[242:245], v[92:95]
	v_mfma_f32_16x16x32_bf16 v[88:91], v[76:79], v[242:245], v[88:91]
	s_setprio 0
	s_setprio 1
	v_mfma_f32_16x16x32_bf16 v[132:135], v[154:157], v[176:179], v[132:135]
	v_mfma_f32_16x16x32_bf16 v[128:131], v[168:171], v[176:179], v[128:131]
	v_mfma_f32_16x16x32_bf16 v[116:119], v[154:157], v[184:187], v[116:119]
	v_mfma_f32_16x16x32_bf16 v[112:115], v[168:171], v[184:187], v[112:115]
	v_mfma_f32_16x16x32_bf16 v[100:103], v[154:157], v[230:233], v[100:103]
	v_mfma_f32_16x16x32_bf16 v[96:99], v[168:171], v[230:233], v[96:99]
	v_mfma_f32_16x16x32_bf16 v[84:87], v[154:157], v[238:241], v[84:87]
	v_mfma_f32_16x16x32_bf16 v[80:83], v[168:171], v[238:241], v[80:83]
	v_mfma_f32_16x16x32_bf16 v[132:135], v[164:167], v[180:183], v[132:135]
	v_mfma_f32_16x16x32_bf16 v[128:131], v[172:175], v[180:183], v[128:131]
	v_mfma_f32_16x16x32_bf16 v[116:119], v[164:167], v[194:197], v[116:119]
	v_mfma_f32_16x16x32_bf16 v[112:115], v[172:175], v[194:197], v[112:115]
	v_mfma_f32_16x16x32_bf16 v[100:103], v[164:167], v[234:237], v[100:103]
	v_mfma_f32_16x16x32_bf16 v[96:99], v[172:175], v[234:237], v[96:99]
	v_mfma_f32_16x16x32_bf16 v[84:87], v[164:167], v[242:245], v[84:87]
	v_mfma_f32_16x16x32_bf16 v[80:83], v[172:175], v[242:245], v[80:83]
	s_setprio 0
	s_barrier
	ds_read_b128 v[176:179], v163 offset:49152
	ds_read_b128 v[180:183], v163 offset:50176
	ds_read_b128 v[184:187], v163 offset:51200
	ds_read_b128 v[194:197], v163 offset:52224
	ds_read_b128 v[230:233], v163 offset:53248
	ds_read_b128 v[234:237], v163 offset:54272
	ds_read_b128 v[238:241], v163 offset:55296
	ds_read_b128 v[242:245], v163 offset:56320
	s_add_i32 s52, s60, s69
	s_mov_b32 m0, s52
	v_lshl_add_u64 v[158:159], v[158:159], 0, s[94:95]
	global_load_lds_dwordx4 v[158:159], off
	s_add_i32 m0, s52, 0x2000
	s_add_u32 s50, s50, 0x40080
	v_lshl_add_u64 v[158:159], v[246:247], 0, s[94:95]
	s_addc_u32 s51, s51, 0
	s_add_i32 s52, s61, s69
	global_load_lds_dwordx4 v[158:159], off
	s_waitcnt vmcnt(4)
	s_waitcnt lgkmcnt(0)
	s_barrier
	s_setprio 1
	s_waitcnt lgkmcnt(0)
	v_mfma_f32_16x16x32_bf16 v[60:63], v[64:67], v[176:179], v[60:63]
	v_mfma_f32_16x16x32_bf16 v[56:59], v[72:75], v[176:179], v[56:59]
	s_mov_b32 m0, s52
	v_lshl_add_u64 v[158:159], s[50:51], 0, v[188:189]
	global_load_lds_dwordx4 v[158:159], off
	v_mfma_f32_16x16x32_bf16 v[44:47], v[64:67], v[184:187], v[44:47]
	v_mfma_f32_16x16x32_bf16 v[40:43], v[72:75], v[184:187], v[40:43]
	v_mfma_f32_16x16x32_bf16 v[28:31], v[64:67], v[230:233], v[28:31]
	v_mfma_f32_16x16x32_bf16 v[24:27], v[72:75], v[230:233], v[24:27]
	v_mfma_f32_16x16x32_bf16 v[12:15], v[64:67], v[238:241], v[12:15]
	v_mfma_f32_16x16x32_bf16 v[8:11], v[72:75], v[238:241], v[8:11]
	v_mfma_f32_16x16x32_bf16 v[60:63], v[68:71], v[180:183], v[60:63]
	v_mfma_f32_16x16x32_bf16 v[56:59], v[76:79], v[180:183], v[56:59]
	s_add_i32 m0, s52, 0x2000
	v_lshl_add_u64 v[158:159], s[50:51], 0, v[148:149]
	global_load_lds_dwordx4 v[158:159], off
	v_mfma_f32_16x16x32_bf16 v[44:47], v[68:71], v[194:197], v[44:47]
	v_mfma_f32_16x16x32_bf16 v[40:43], v[76:79], v[194:197], v[40:43]
	v_mfma_f32_16x16x32_bf16 v[28:31], v[68:71], v[234:237], v[28:31]
	v_mfma_f32_16x16x32_bf16 v[24:27], v[76:79], v[234:237], v[24:27]
	v_mfma_f32_16x16x32_bf16 v[12:15], v[68:71], v[242:245], v[12:15]
	v_mfma_f32_16x16x32_bf16 v[8:11], v[76:79], v[242:245], v[8:11]
	s_setprio 0
	s_setprio 1
	v_mfma_f32_16x16x32_bf16 v[52:55], v[154:157], v[176:179], v[52:55]
	v_mfma_f32_16x16x32_bf16 v[48:51], v[168:171], v[176:179], v[48:51]
	s_mov_b32 m0, s2
	v_lshl_add_u64 v[158:159], v[248:249], 0, s[94:95]
	global_load_lds_dwordx4 v[158:159], off
	v_mfma_f32_16x16x32_bf16 v[36:39], v[154:157], v[184:187], v[36:39]
	v_mfma_f32_16x16x32_bf16 v[32:35], v[168:171], v[184:187], v[32:35]
	v_mfma_f32_16x16x32_bf16 v[20:23], v[154:157], v[230:233], v[20:23]
	v_mfma_f32_16x16x32_bf16 v[16:19], v[168:171], v[230:233], v[16:19]
	v_mfma_f32_16x16x32_bf16 v[4:7], v[154:157], v[238:241], v[4:7]
	v_mfma_f32_16x16x32_bf16 v[0:3], v[168:171], v[238:241], v[0:3]
	v_mfma_f32_16x16x32_bf16 v[52:55], v[164:167], v[180:183], v[52:55]
	v_mfma_f32_16x16x32_bf16 v[48:51], v[172:175], v[180:183], v[48:51]
	s_mov_b32 m0, s4
	v_lshl_add_u64 v[158:159], v[250:251], 0, s[94:95]
	global_load_lds_dwordx4 v[158:159], off
	v_mfma_f32_16x16x32_bf16 v[36:39], v[164:167], v[194:197], v[36:39]
	v_mfma_f32_16x16x32_bf16 v[32:35], v[172:175], v[194:197], v[32:35]
	v_mfma_f32_16x16x32_bf16 v[20:23], v[164:167], v[234:237], v[20:23]
	v_mfma_f32_16x16x32_bf16 v[16:19], v[172:175], v[234:237], v[16:19]
	v_mfma_f32_16x16x32_bf16 v[4:7], v[164:167], v[242:245], v[4:7]
	v_mfma_f32_16x16x32_bf16 v[0:3], v[172:175], v[242:245], v[0:3]
	s_setprio 0
	s_barrier
	s_add_i32 s59, s59, 2
	s_add_u32 s8, s8, 0x100
	s_addc_u32 s9, s9, 0
	s_add_u32 s55, s55, 0x100
	s_addc_u32 s58, s58, 0
	s_cmp_gt_u32 s59, 13
	s_cbranch_scc0 .LBB0_171
	s_and_b64 vcc, exec, s[30:31]
	s_cbranch_vccz .LBB0_174
	s_barrier

; #define PG8_STAGE(bufoff, gbase, voff) do { _Pragma("unroll") for (int _i = 0; _i < 2; ++_i) \
;         __builtin_amdgcn_global_load_lds((const unsigned*)((const char*)(gbase) + (voff)[_i]), (PG8_LAS unsigned*)(lds + (bufoff) + ldsw + _i * 8192), 16, 0, 0); } while (0)
; #define PG8_LDA(dst, b, h) do { _Pragma("unroll") for (int m = 0; m < 4; ++m) _Pragma("unroll") for (int k = 0; k < 2; ++k) dst[m][k] = *(const PG8_LAS bf16x8*)(lds + PG8_SA(b, h) + aoff + m * 2048 + k * 1024); } while (0)
; #define PG8_LDB(dst, b, h) do { _Pragma("unroll") for (int n = 0; n < 2; ++n) _Pragma("unroll") for (int k = 0; k < 2; ++k) dst[n][k] = *(const PG8_LAS bf16x8*)(lds + PG8_SB(b, h) + boff + n * 2048 + k * 1024); } while (0)
; #define PG8_MMA(ai, bj, At, Bt) do { __builtin_amdgcn_s_setprio(1); _Pragma("unroll") for (int m = 0; m < 4; ++m) _Pragma("unroll") for (int n = 0; n < 2; ++n) _Pragma("unroll") for (int k = 0; k < 2; ++k) \
;         acc[ai][bj][m][n] = __builtin_amdgcn_mfma_f32_16x16x32_bf16(Bt[n][k], At[m][k], acc[ai][bj][m][n], 0, 0, 0); __builtin_amdgcn_s_setprio(0); } while (0)
; #define PG8_WAIT_V(n) asm volatile("s_waitcnt vmcnt(" #n ")" ::: "memory")
; #define PG8_WAIT_L(n) asm volatile("s_waitcnt lgkmcnt(" #n ")" ::: "memory")
; template <class Epi, class Sched, bool ALIGN_EPI = false, bool SP2 = false>
; __device__ __forceinline__ void gemm_phase(PG8_LAS unsigned char* lds, const Gemm g, const Sched& S, const Epi& E) {
;     ...
;             const bool last = (t == nt - 2);
;             const char* a1 = cA + (size_t)(t + 1) * kstep;
;             const char* a2 = last ? nA : cA + (size_t)(t + 2) * kstep; const char* b2 = last ? nB : cB + (size_t)(t + 2) * kstep;
;             const char* a3 = a2 + kstep; const char* b3 = b2 + kstep;
;             if (last && has_next) S.a_ready(nxt);
;             if constexpr (SP2) {
;             PG8_LDB(B0, 0, 0); PG8_LDB(B1, 0, 1); PG8_SCHED; PG8_LDA(At, 0, 0); PG8_STAGE(PG8_SA(1, 1), a1 + hstepA, voffA);
;             PG8_WAIT_V(8); PG8_WAIT_L(0); PG8_BAR; PG8_MMA(0, 0, At, B0); PG8_MMA(0, 1, At, B1); PG8_BAR; PG8_SCHED;
;             PG8_LDA(At, 0, 1); PG8_STAGE(PG8_SB(0, 0), b2, voffB); PG8_STAGE(PG8_SB(0, 1), b2 + hstepB, voffB); PG8_STAGE(PG8_SA(0, 0), a2, voffA);
;             PG8_WAIT_V(8); PG8_WAIT_L(0); PG8_BAR; PG8_MMA(1, 0, At, B0); PG8_MMA(1, 1, At, B1); PG8_BAR; PG8_SCHED;
.LBB0_712:
	v_add_u32_e32 v154, 0x10000, v144
	v_add_u32_e32 v170, 0x14000, v144
	ds_read_b128 v[138:141], v154
	ds_read_b128 v[146:149], v154 offset:1024
	ds_read_b128 v[150:153], v154 offset:2048
	ds_read_b128 v[154:157], v154 offset:3072
	ds_read_b128 v[158:161], v170
	ds_read_b128 v[162:165], v170 offset:1024
	ds_read_b128 v[166:169], v170 offset:2048
	ds_read_b128 v[170:173], v170 offset:3072
	ds_read_b128 v[174:177], v145
	ds_read_b128 v[178:181], v145 offset:1024
	ds_read_b128 v[182:185], v145 offset:2048
	ds_read_b128 v[192:195], v145 offset:3072
	ds_read_b128 v[230:233], v145 offset:4096
	ds_read_b128 v[234:237], v145 offset:5120
	ds_read_b128 v[238:241], v145 offset:6144
	ds_read_b128 v[242:245], v145 offset:7168
	s_add_u32 s28, s26, 0xfffc0080
	s_addc_u32 s29, s27, -1
	s_add_i32 s33, 0, 0x10000
	s_cmp_eq_u32 s19, 12
	s_cselect_b32 s31, s1, s29
	s_cselect_b32 s30, s2, s28
	s_cselect_b32 s29, s3, s17
	s_cselect_b32 s28, s4, s9
	s_add_i32 s51, 0, 0x14000
	s_add_i32 m0, s25, 0xc000
	v_lshl_add_u64 v[186:187], s[26:27], 0, v[134:135]
	global_load_lds_dwordx4 v[186:187], off
	s_add_i32 m0, s25, 0xe000
	v_lshl_add_u64 v[186:187], s[26:27], 0, v[136:137]
	global_load_lds_dwordx4 v[186:187], off
	s_waitcnt vmcnt(8)
	s_waitcnt lgkmcnt(0)
	s_barrier
	s_setprio 1
	s_waitcnt lgkmcnt(0)
	v_mfma_f32_16x16x32_bf16 v[124:127], v[138:141], v[174:177], v[124:127]
	v_mfma_f32_16x16x32_bf16 v[120:123], v[150:153], v[174:177], v[120:123]
	v_mfma_f32_16x16x32_bf16 v[108:111], v[138:141], v[182:185], v[108:111]
	v_mfma_f32_16x16x32_bf16 v[104:107], v[150:153], v[182:185], v[104:107]
	v_mfma_f32_16x16x32_bf16 v[92:95], v[138:141], v[230:233], v[92:95]
	v_mfma_f32_16x16x32_bf16 v[88:91], v[150:153], v[230:233], v[88:91]
	v_mfma_f32_16x16x32_bf16 v[76:79], v[138:141], v[238:241], v[76:79]
	v_mfma_f32_16x16x32_bf16 v[72:75], v[150:153], v[238:241], v[72:75]
	v_mfma_f32_16x16x32_bf16 v[124:127], v[146:149], v[178:181], v[124:127]
	v_mfma_f32_16x16x32_bf16 v[120:123], v[154:157], v[178:181], v[120:123]
	v_mfma_f32_16x16x32_bf16 v[108:111], v[146:149], v[192:195], v[108:111]
	v_mfma_f32_16x16x32_bf16 v[104:107], v[154:157], v[192:195], v[104:107]
	v_mfma_f32_16x16x32_bf16 v[92:95], v[146:149], v[234:237], v[92:95]
	v_mfma_f32_16x16x32_bf16 v[88:91], v[154:157], v[234:237], v[88:91]
	v_mfma_f32_16x16x32_bf16 v[76:79], v[146:149], v[242:245], v[76:79]
	v_mfma_f32_16x16x32_bf16 v[72:75], v[154:157], v[242:245], v[72:75]
	s_setprio 0
	s_setprio 1
	v_mfma_f32_16x16x32_bf16 v[116:119], v[158:161], v[174:177], v[116:119]
	v_mfma_f32_16x16x32_bf16 v[112:115], v[166:169], v[174:177], v[112:115]
	v_mfma_f32_16x16x32_bf16 v[100:103], v[158:161], v[182:185], v[100:103]
	v_mfma_f32_16x16x32_bf16 v[96:99], v[166:169], v[182:185], v[96:99]
	v_mfma_f32_16x16x32_bf16 v[84:87], v[158:161], v[230:233], v[84:87]
	v_mfma_f32_16x16x32_bf16 v[80:83], v[166:169], v[230:233], v[80:83]
	v_mfma_f32_16x16x32_bf16 v[68:71], v[158:161], v[238:241], v[68:71]
	v_mfma_f32_16x16x32_bf16 v[64:67], v[166:169], v[238:241], v[64:67]
	v_mfma_f32_16x16x32_bf16 v[116:119], v[162:165], v[178:181], v[116:119]
	v_mfma_f32_16x16x32_bf16 v[112:115], v[170:173], v[178:181], v[112:115]
	v_mfma_f32_16x16x32_bf16 v[100:103], v[162:165], v[192:195], v[100:103]
	v_mfma_f32_16x16x32_bf16 v[96:99], v[170:173], v[192:195], v[96:99]
	v_mfma_f32_16x16x32_bf16 v[84:87], v[162:165], v[234:237], v[84:87]
	v_mfma_f32_16x16x32_bf16 v[80:83], v[170:173], v[234:237], v[80:83]
	v_mfma_f32_16x16x32_bf16 v[68:71], v[162:165], v[242:245], v[68:71]
	v_mfma_f32_16x16x32_bf16 v[64:67], v[170:173], v[242:245], v[64:67]
	s_setprio 0
	s_barrier
	ds_read_b128 v[174:177], v145 offset:16384
	ds_read_b128 v[178:181], v145 offset:17408
	ds_read_b128 v[182:185], v145 offset:18432
	ds_read_b128 v[192:195], v145 offset:19456
	ds_read_b128 v[230:233], v145 offset:20480
	ds_read_b128 v[234:237], v145 offset:21504
	ds_read_b128 v[238:241], v145 offset:22528
	ds_read_b128 v[242:245], v145 offset:23552
	s_add_i32 s33, s33, s39
	s_mov_b32 m0, s33
	v_lshl_add_u64 v[186:187], s[28:29], 0, v[188:189]
	global_load_lds_dwordx4 v[186:187], off
	s_add_i32 m0, s33, 0x2000
	s_add_u32 s52, s28, 0x40000
	v_lshl_add_u64 v[196:197], s[28:29], 0, v[132:133]
	s_addc_u32 s53, s29, 0
	s_add_i32 s33, s51, s39
	global_load_lds_dwordx4 v[196:197], off
	s_waitcnt vmcnt(4)
	s_waitcnt lgkmcnt(0)
	s_barrier
; #define PG8_STAGE(bufoff, gbase, voff) do { _Pragma("unroll") for (int _i = 0; _i < 2; ++_i) \
;         __builtin_amdgcn_global_load_lds((const unsigned*)((const char*)(gbase) + (voff)[_i]), (PG8_LAS unsigned*)(lds + (bufoff) + ldsw + _i * 8192), 16, 0, 0); } while (0)
; #define PG8_LDA(dst, b, h) do { _Pragma("unroll") for (int m = 0; m < 4; ++m) _Pragma("unroll") for (int k = 0; k < 2; ++k) dst[m][k] = *(const PG8_LAS bf16x8*)(lds + PG8_SA(b, h) + aoff + m * 2048 + k * 1024); } while (0)
; #define PG8_LDB(dst, b, h) do { _Pragma("unroll") for (int n = 0; n < 2; ++n) _Pragma("unroll") for (int k = 0; k < 2; ++k) dst[n][k] = *(const PG8_LAS bf16x8*)(lds + PG8_SB(b, h) + boff + n * 2048 + k * 1024); } while (0)
; #define PG8_MMA(ai, bj, At, Bt) do { __builtin_amdgcn_s_setprio(1); _Pragma("unroll") for (int m = 0; m < 4; ++m) _Pragma("unroll") for (int n = 0; n < 2; ++n) _Pragma("unroll") for (int k = 0; k < 2; ++k) \
;         acc[ai][bj][m][n] = __builtin_amdgcn_mfma_f32_16x16x32_bf16(Bt[n][k], At[m][k], acc[ai][bj][m][n], 0, 0, 0); __builtin_amdgcn_s_setprio(0); } while (0)
; #define PG8_WAIT_V(n) asm volatile("s_waitcnt vmcnt(" #n ")" ::: "memory")
; #define PG8_WAIT_L(n) asm volatile("s_waitcnt lgkmcnt(" #n ")" ::: "memory")
; #define PG8_BAR __builtin_amdgcn_s_barrier()
; #define PG8_SCHED __builtin_amdgcn_sched_barrier(0)
; template <class Epi, class Sched, bool ALIGN_EPI = false, bool SP2 = false>
; __device__ __forceinline__ void gemm_phase(PG8_LAS unsigned char* lds, const Gemm g, const Sched& S, const Epi& E) {
;     ...
;             PG8_WAIT_V(8); PG8_WAIT_L(0); PG8_BAR; PG8_MMA(1, 0, At, B0); PG8_MMA(1, 1, At, B1); PG8_BAR; PG8_SCHED;
;             PG8_LDB(B0, 1, 0); PG8_LDB(B1, 1, 1); PG8_SCHED; PG8_LDA(At, 1, 0); PG8_STAGE(PG8_SA(0, 1), a2 + hstepA, voffA);
;             PG8_WAIT_V(8); PG8_WAIT_L(0); PG8_BAR; PG8_MMA(0, 0, At, B0); PG8_MMA(0, 1, At, B1); PG8_BAR; PG8_SCHED;
	s_setprio 1
	s_waitcnt lgkmcnt(0)
	v_mfma_f32_16x16x32_bf16 v[60:63], v[138:141], v[174:177], v[60:63]
	v_mfma_f32_16x16x32_bf16 v[56:59], v[150:153], v[174:177], v[56:59]
	v_lshl_add_u64 v[246:247], s[52:53], 0, v[188:189]
	s_mov_b32 m0, s33
	v_lshl_add_u64 v[248:249], s[30:31], 0, v[130:131]
	global_load_lds_dwordx4 v[246:247], off
	v_mfma_f32_16x16x32_bf16 v[44:47], v[138:141], v[182:185], v[44:47]
	v_mfma_f32_16x16x32_bf16 v[40:43], v[150:153], v[182:185], v[40:43]
	v_mfma_f32_16x16x32_bf16 v[28:31], v[138:141], v[230:233], v[28:31]
	v_mfma_f32_16x16x32_bf16 v[24:27], v[150:153], v[230:233], v[24:27]
	v_mfma_f32_16x16x32_bf16 v[12:15], v[138:141], v[238:241], v[12:15]
	v_mfma_f32_16x16x32_bf16 v[8:11], v[150:153], v[238:241], v[8:11]
	v_mfma_f32_16x16x32_bf16 v[60:63], v[146:149], v[178:181], v[60:63]
	v_mfma_f32_16x16x32_bf16 v[56:59], v[154:157], v[178:181], v[56:59]
	s_add_i32 m0, s33, 0x2000
	v_lshl_add_u64 v[246:247], s[52:53], 0, v[132:133]
	global_load_lds_dwordx4 v[246:247], off
	v_mfma_f32_16x16x32_bf16 v[44:47], v[146:149], v[192:195], v[44:47]
	v_mfma_f32_16x16x32_bf16 v[40:43], v[154:157], v[192:195], v[40:43]
	v_mfma_f32_16x16x32_bf16 v[28:31], v[146:149], v[234:237], v[28:31]
	v_mfma_f32_16x16x32_bf16 v[24:27], v[154:157], v[234:237], v[24:27]
	v_mfma_f32_16x16x32_bf16 v[12:15], v[146:149], v[242:245], v[12:15]
	v_mfma_f32_16x16x32_bf16 v[8:11], v[154:157], v[242:245], v[8:11]
	s_setprio 0
	s_setprio 1
	v_mfma_f32_16x16x32_bf16 v[52:55], v[158:161], v[174:177], v[52:55]
	v_mfma_f32_16x16x32_bf16 v[48:51], v[166:169], v[174:177], v[48:51]
	s_mov_b32 m0, s25
	v_lshl_add_u64 v[246:247], s[30:31], 0, v[128:129]
	global_load_lds_dwordx4 v[246:247], off
	v_mfma_f32_16x16x32_bf16 v[36:39], v[158:161], v[182:185], v[36:39]
	v_mfma_f32_16x16x32_bf16 v[32:35], v[166:169], v[182:185], v[32:35]
	v_mfma_f32_16x16x32_bf16 v[20:23], v[158:161], v[230:233], v[20:23]
	v_mfma_f32_16x16x32_bf16 v[16:19], v[166:169], v[230:233], v[16:19]
	v_mfma_f32_16x16x32_bf16 v[4:7], v[158:161], v[238:241], v[4:7]
	v_mfma_f32_16x16x32_bf16 v[0:3], v[166:169], v[238:241], v[0:3]
	v_mfma_f32_16x16x32_bf16 v[52:55], v[162:165], v[178:181], v[52:55]
	v_mfma_f32_16x16x32_bf16 v[48:51], v[170:173], v[178:181], v[48:51]
	s_mov_b32 m0, s40
	s_nop 0
	global_load_lds_dwordx4 v[248:249], off
	v_mfma_f32_16x16x32_bf16 v[36:39], v[162:165], v[192:195], v[36:39]
	v_mfma_f32_16x16x32_bf16 v[32:35], v[170:173], v[192:195], v[32:35]
	v_mfma_f32_16x16x32_bf16 v[20:23], v[162:165], v[234:237], v[20:23]
	v_mfma_f32_16x16x32_bf16 v[16:19], v[170:173], v[234:237], v[16:19]
	v_mfma_f32_16x16x32_bf16 v[4:7], v[162:165], v[242:245], v[4:7]
	v_mfma_f32_16x16x32_bf16 v[0:3], v[170:173], v[242:245], v[0:3]
	s_setprio 0
	s_barrier
	v_add_u32_e32 v154, 0x18000, v144
	v_add_u32_e32 v170, 0x1c000, v144
	ds_read_b128 v[138:141], v154
	ds_read_b128 v[146:149], v154 offset:1024
	ds_read_b128 v[150:153], v154 offset:2048
	ds_read_b128 v[154:157], v154 offset:3072
	ds_read_b128 v[158:161], v170
	ds_read_b128 v[162:165], v170 offset:1024
	ds_read_b128 v[166:169], v170 offset:2048
	ds_read_b128 v[170:173], v170 offset:3072
	ds_read_b128 v[174:177], v145 offset:32768
	ds_read_b128 v[178:181], v145 offset:33792
	ds_read_b128 v[182:185], v145 offset:34816
	ds_read_b128 v[192:195], v145 offset:35840
	ds_read_b128 v[230:233], v145 offset:36864
	ds_read_b128 v[234:237], v145 offset:37888
	ds_read_b128 v[238:241], v145 offset:38912
	ds_read_b128 v[242:245], v145 offset:39936
	s_add_i32 s33, 0, 0x18000
	s_add_i32 s51, 0, 0x1c000
	s_add_u32 s30, s30, 0x40000
	s_addc_u32 s31, s31, 0
	s_mov_b32 m0, s41
	v_lshl_add_u64 v[250:251], s[30:31], 0, v[128:129]
	global_load_lds_dwordx4 v[250:251], off
	s_mov_b32 m0, s42
	v_lshl_add_u64 v[250:251], s[30:31], 0, v[130:131]
	global_load_lds_dwordx4 v[250:251], off
	s_waitcnt vmcnt(8)
	s_waitcnt lgkmcnt(0)
	s_barrier
; #define PG8_STAGE(bufoff, gbase, voff) do { _Pragma("unroll") for (int _i = 0; _i < 2; ++_i) \
;         __builtin_amdgcn_global_load_lds((const unsigned*)((const char*)(gbase) + (voff)[_i]), (PG8_LAS unsigned*)(lds + (bufoff) + ldsw + _i * 8192), 16, 0, 0); } while (0)
; #define PG8_LDA(dst, b, h) do { _Pragma("unroll") for (int m = 0; m < 4; ++m) _Pragma("unroll") for (int k = 0; k < 2; ++k) dst[m][k] = *(const PG8_LAS bf16x8*)(lds + PG8_SA(b, h) + aoff + m * 2048 + k * 1024); } while (0)
; #define PG8_MMA(ai, bj, At, Bt) do { __builtin_amdgcn_s_setprio(1); _Pragma("unroll") for (int m = 0; m < 4; ++m) _Pragma("unroll") for (int n = 0; n < 2; ++n) _Pragma("unroll") for (int k = 0; k < 2; ++k) \
;         acc[ai][bj][m][n] = __builtin_amdgcn_mfma_f32_16x16x32_bf16(Bt[n][k], At[m][k], acc[ai][bj][m][n], 0, 0, 0); __builtin_amdgcn_s_setprio(0); } while (0)
; #define PG8_WAIT_V(n) asm volatile("s_waitcnt vmcnt(" #n ")" ::: "memory")
; #define PG8_WAIT_L(n) asm volatile("s_waitcnt lgkmcnt(" #n ")" ::: "memory")
; #define PG8_BAR __builtin_amdgcn_s_barrier()
; #define PG8_SCHED __builtin_amdgcn_sched_barrier(0)
; template <class Epi, class Sched, bool ALIGN_EPI = false, bool SP2 = false>
; __device__ __forceinline__ void gemm_phase(PG8_LAS unsigned char* lds, const Gemm g, const Sched& S, const Epi& E) {
;     ...
;         for (int t = 0; t < nt; t += 2) {
;     ...
;             PG8_WAIT_V(8); PG8_WAIT_L(0); PG8_BAR; PG8_MMA(0, 0, At, B0); PG8_MMA(0, 1, At, B1); PG8_BAR; PG8_SCHED;
;             PG8_LDA(At, 1, 1); PG8_STAGE(PG8_SB(1, 0), b3, voffB); PG8_STAGE(PG8_SB(1, 1), b3 + hstepB, voffB); PG8_STAGE(PG8_SA(1, 0), a3, voffA);
;             PG8_WAIT_V(8); PG8_WAIT_L(0); PG8_BAR; PG8_MMA(1, 0, At, B0); PG8_MMA(1, 1, At, B1); PG8_BAR; PG8_SCHED;
	s_setprio 1
	s_waitcnt lgkmcnt(0)
	v_mfma_f32_16x16x32_bf16 v[124:127], v[138:141], v[174:177], v[124:127]
	v_mfma_f32_16x16x32_bf16 v[120:123], v[150:153], v[174:177], v[120:123]
	v_mfma_f32_16x16x32_bf16 v[108:111], v[138:141], v[182:185], v[108:111]
	v_mfma_f32_16x16x32_bf16 v[104:107], v[150:153], v[182:185], v[104:107]
	v_mfma_f32_16x16x32_bf16 v[92:95], v[138:141], v[230:233], v[92:95]
	v_mfma_f32_16x16x32_bf16 v[88:91], v[150:153], v[230:233], v[88:91]
	v_mfma_f32_16x16x32_bf16 v[76:79], v[138:141], v[238:241], v[76:79]
	v_mfma_f32_16x16x32_bf16 v[72:75], v[150:153], v[238:241], v[72:75]
	v_mfma_f32_16x16x32_bf16 v[124:127], v[146:149], v[178:181], v[124:127]
	v_mfma_f32_16x16x32_bf16 v[120:123], v[154:157], v[178:181], v[120:123]
	v_mfma_f32_16x16x32_bf16 v[108:111], v[146:149], v[192:195], v[108:111]
	v_mfma_f32_16x16x32_bf16 v[104:107], v[154:157], v[192:195], v[104:107]
	v_mfma_f32_16x16x32_bf16 v[92:95], v[146:149], v[234:237], v[92:95]
	v_mfma_f32_16x16x32_bf16 v[88:91], v[154:157], v[234:237], v[88:91]
	v_mfma_f32_16x16x32_bf16 v[76:79], v[146:149], v[242:245], v[76:79]
	v_mfma_f32_16x16x32_bf16 v[72:75], v[154:157], v[242:245], v[72:75]
	s_setprio 0
	s_setprio 1
	v_mfma_f32_16x16x32_bf16 v[116:119], v[158:161], v[174:177], v[116:119]
	v_mfma_f32_16x16x32_bf16 v[112:115], v[166:169], v[174:177], v[112:115]
	v_mfma_f32_16x16x32_bf16 v[100:103], v[158:161], v[182:185], v[100:103]
	v_mfma_f32_16x16x32_bf16 v[96:99], v[166:169], v[182:185], v[96:99]
	v_mfma_f32_16x16x32_bf16 v[84:87], v[158:161], v[230:233], v[84:87]
	v_mfma_f32_16x16x32_bf16 v[80:83], v[166:169], v[230:233], v[80:83]
	v_mfma_f32_16x16x32_bf16 v[68:71], v[158:161], v[238:241], v[68:71]
	v_mfma_f32_16x16x32_bf16 v[64:67], v[166:169], v[238:241], v[64:67]
	v_mfma_f32_16x16x32_bf16 v[116:119], v[162:165], v[178:181], v[116:119]
	v_mfma_f32_16x16x32_bf16 v[112:115], v[170:173], v[178:181], v[112:115]
	v_mfma_f32_16x16x32_bf16 v[100:103], v[162:165], v[192:195], v[100:103]
	v_mfma_f32_16x16x32_bf16 v[96:99], v[170:173], v[192:195], v[96:99]
	v_mfma_f32_16x16x32_bf16 v[84:87], v[162:165], v[234:237], v[84:87]
	v_mfma_f32_16x16x32_bf16 v[80:83], v[170:173], v[234:237], v[80:83]
	v_mfma_f32_16x16x32_bf16 v[68:71], v[162:165], v[242:245], v[68:71]
	v_mfma_f32_16x16x32_bf16 v[64:67], v[170:173], v[242:245], v[64:67]
	s_setprio 0
	s_barrier
	ds_read_b128 v[174:177], v145 offset:49152
	ds_read_b128 v[178:181], v145 offset:50176
	ds_read_b128 v[182:185], v145 offset:51200
	ds_read_b128 v[192:195], v145 offset:52224
	ds_read_b128 v[230:233], v145 offset:53248
	ds_read_b128 v[234:237], v145 offset:54272
	ds_read_b128 v[238:241], v145 offset:55296
	ds_read_b128 v[242:245], v145 offset:56320
	s_add_i32 s30, s33, s39
	s_mov_b32 m0, s30
	v_lshl_add_u64 v[186:187], v[186:187], 0, s[94:95]
	global_load_lds_dwordx4 v[186:187], off
	s_add_i32 m0, s30, 0x2000
	s_add_u32 s28, s28, 0x40080
	v_lshl_add_u64 v[186:187], v[196:197], 0, s[94:95]
	s_addc_u32 s29, s29, 0
	s_add_i32 s30, s51, s39
	global_load_lds_dwordx4 v[186:187], off
	s_waitcnt vmcnt(4)
	s_waitcnt lgkmcnt(0)
	s_barrier
	s_setprio 1
	s_waitcnt lgkmcnt(0)
	v_mfma_f32_16x16x32_bf16 v[60:63], v[138:141], v[174:177], v[60:63]
	v_mfma_f32_16x16x32_bf16 v[56:59], v[150:153], v[174:177], v[56:59]
	s_mov_b32 m0, s30
	v_lshl_add_u64 v[186:187], s[28:29], 0, v[188:189]
	global_load_lds_dwordx4 v[186:187], off
	v_mfma_f32_16x16x32_bf16 v[44:47], v[138:141], v[182:185], v[44:47]
	v_mfma_f32_16x16x32_bf16 v[40:43], v[150:153], v[182:185], v[40:43]
	v_mfma_f32_16x16x32_bf16 v[28:31], v[138:141], v[230:233], v[28:31]
	v_mfma_f32_16x16x32_bf16 v[24:27], v[150:153], v[230:233], v[24:27]
	v_mfma_f32_16x16x32_bf16 v[12:15], v[138:141], v[238:241], v[12:15]
	v_mfma_f32_16x16x32_bf16 v[8:11], v[150:153], v[238:241], v[8:11]
	v_mfma_f32_16x16x32_bf16 v[60:63], v[146:149], v[178:181], v[60:63]
	v_mfma_f32_16x16x32_bf16 v[56:59], v[154:157], v[178:181], v[56:59]
	s_add_i32 m0, s30, 0x2000
	v_lshl_add_u64 v[186:187], s[28:29], 0, v[132:133]
	global_load_lds_dwordx4 v[186:187], off
	v_mfma_f32_16x16x32_bf16 v[44:47], v[146:149], v[192:195], v[44:47]
	v_mfma_f32_16x16x32_bf16 v[40:43], v[154:157], v[192:195], v[40:43]
	v_mfma_f32_16x16x32_bf16 v[28:31], v[146:149], v[234:237], v[28:31]
	v_mfma_f32_16x16x32_bf16 v[24:27], v[154:157], v[234:237], v[24:27]
	v_mfma_f32_16x16x32_bf16 v[12:15], v[146:149], v[242:245], v[12:15]
	v_mfma_f32_16x16x32_bf16 v[8:11], v[154:157], v[242:245], v[8:11]
	s_setprio 0
	s_setprio 1
	v_mfma_f32_16x16x32_bf16 v[52:55], v[158:161], v[174:177], v[52:55]
	v_mfma_f32_16x16x32_bf16 v[48:51], v[166:169], v[174:177], v[48:51]
	s_mov_b32 m0, s47
	v_lshl_add_u64 v[186:187], v[246:247], 0, s[94:95]
	global_load_lds_dwordx4 v[186:187], off
	v_mfma_f32_16x16x32_bf16 v[36:39], v[158:161], v[182:185], v[36:39]
	v_mfma_f32_16x16x32_bf16 v[32:35], v[166:169], v[182:185], v[32:35]
	v_mfma_f32_16x16x32_bf16 v[20:23], v[158:161], v[230:233], v[20:23]
	v_mfma_f32_16x16x32_bf16 v[16:19], v[166:169], v[230:233], v[16:19]
	v_mfma_f32_16x16x32_bf16 v[4:7], v[158:161], v[238:241], v[4:7]
	v_mfma_f32_16x16x32_bf16 v[0:3], v[166:169], v[238:241], v[0:3]
	v_mfma_f32_16x16x32_bf16 v[52:55], v[162:165], v[178:181], v[52:55]
	v_mfma_f32_16x16x32_bf16 v[48:51], v[170:173], v[178:181], v[48:51]
	s_mov_b32 m0, s48
	v_lshl_add_u64 v[186:187], v[248:249], 0, s[94:95]
	global_load_lds_dwordx4 v[186:187], off
	v_mfma_f32_16x16x32_bf16 v[36:39], v[162:165], v[192:195], v[36:39]
	v_mfma_f32_16x16x32_bf16 v[32:35], v[170:173], v[192:195], v[32:35]
	v_mfma_f32_16x16x32_bf16 v[20:23], v[162:165], v[234:237], v[20:23]
	v_mfma_f32_16x16x32_bf16 v[16:19], v[170:173], v[234:237], v[16:19]
	v_mfma_f32_16x16x32_bf16 v[4:7], v[162:165], v[242:245], v[4:7]
	v_mfma_f32_16x16x32_bf16 v[0:3], v[170:173], v[242:245], v[0:3]
	s_setprio 0
	s_barrier
	s_add_i32 s19, s19, 2
	s_add_u32 s26, s26, 0x100
	s_addc_u32 s27, s27, 0
	s_add_u32 s9, s9, 0x100
	s_addc_u32 s17, s17, 0
	s_cmp_gt_u32 s19, 13
	s_cbranch_scc0 .LBB0_712
	s_and_b64 vcc, exec, s[14:15]
	s_cbranch_vccz .LBB0_715
	s_barrier

; #define PG8_STAGE(bufoff, gbase, voff) do { _Pragma("unroll") for (int _i = 0; _i < 2; ++_i) \
;         __builtin_amdgcn_global_load_lds((const unsigned*)((const char*)(gbase) + (voff)[_i]), (PG8_LAS unsigned*)(lds + (bufoff) + ldsw + _i * 8192), 16, 0, 0); } while (0)
; #define PG8_LDA(dst, b, h) do { _Pragma("unroll") for (int m = 0; m < 4; ++m) _Pragma("unroll") for (int k = 0; k < 2; ++k) dst[m][k] = *(const PG8_LAS bf16x8*)(lds + PG8_SA(b, h) + aoff + m * 2048 + k * 1024); } while (0)
; #define PG8_LDB(dst, b, h) do { _Pragma("unroll") for (int n = 0; n < 2; ++n) _Pragma("unroll") for (int k = 0; k < 2; ++k) dst[n][k] = *(const PG8_LAS bf16x8*)(lds + PG8_SB(b, h) + boff + n * 2048 + k * 1024); } while (0)
; #define PG8_WAIT_V(n) asm volatile("s_waitcnt vmcnt(" #n ")" ::: "memory")
; #define PG8_WAIT_L(n) asm volatile("s_waitcnt lgkmcnt(" #n ")" ::: "memory")
; #define PG8_BAR __builtin_amdgcn_s_barrier()
; #define PG8_SCHED __builtin_amdgcn_sched_barrier(0)
; template <class Epi, class Sched, bool ALIGN_EPI = false, bool SP2 = false>
; __device__ __forceinline__ void gemm_phase(PG8_LAS unsigned char* lds, const Gemm g, const Sched& S, const Epi& E) {
;     ...
;         const char* nA = has_next ? (const char*)g.A + (size_t)nxt.pm * tstepA + (size_t)((nxt.pn / g.kdiv) * g.kmul) * 2 : cA; const char* nB = has_next ? (const char*)g.Bt + (size_t)nxt.pn * tstepB : cB;
; #pragma nounroll
;         for (int t = 0; t < nt; t += 2) {
;             const bool last = (t == nt - 2);
;             const char* a1 = cA + (size_t)(t + 1) * kstep;
;             const char* a2 = last ? nA : cA + (size_t)(t + 2) * kstep; const char* b2 = last ? nB : cB + (size_t)(t + 2) * kstep;
;             const char* a3 = a2 + kstep; const char* b3 = b2 + kstep;
;             if (last && has_next) S.a_ready(nxt);
;             if constexpr (SP2) {
;             PG8_LDB(B0, 0, 0); PG8_LDB(B1, 0, 1); PG8_SCHED; PG8_LDA(At, 0, 0); PG8_STAGE(PG8_SA(1, 1), a1 + hstepA, voffA);
;             PG8_WAIT_V(8); PG8_WAIT_L(0); PG8_BAR; PG8_MMA(0, 0, At, B0); PG8_MMA(0, 1, At, B1); PG8_BAR; PG8_SCHED;
;             PG8_LDA(At, 0, 1); PG8_STAGE(PG8_SB(0, 0), b2, voffB); PG8_STAGE(PG8_SB(0, 1), b2 + hstepB, voffB); PG8_STAGE(PG8_SA(0, 0), a2, voffA);
;             PG8_WAIT_V(8); PG8_WAIT_L(0); PG8_BAR; PG8_MMA(1, 0, At, B0); PG8_MMA(1, 1, At, B1); PG8_BAR; PG8_SCHED;
.LBB0_901:
	v_add_u32_e32 v150, 0x10000, v136
	v_add_u32_e32 v166, 0x14000, v136
	ds_read_b128 v[138:141], v150
	ds_read_b128 v[142:145], v150 offset:1024
	ds_read_b128 v[146:149], v150 offset:2048
	ds_read_b128 v[150:153], v150 offset:3072
	ds_read_b128 v[154:157], v166
	ds_read_b128 v[158:161], v166 offset:1024
	ds_read_b128 v[162:165], v166 offset:2048
	ds_read_b128 v[166:169], v166 offset:3072
	ds_read_b128 v[170:173], v137
	ds_read_b128 v[174:177], v137 offset:1024
	ds_read_b128 v[178:181], v137 offset:2048
	ds_read_b128 v[182:185], v137 offset:3072
	ds_read_b128 v[192:195], v137 offset:4096
	ds_read_b128 v[230:233], v137 offset:5120
	ds_read_b128 v[234:237], v137 offset:6144
	ds_read_b128 v[238:241], v137 offset:7168
	s_add_u32 s44, s34, s38
	s_addc_u32 s45, s35, s39
	s_add_u32 s42, s44, 0x100
	s_addc_u32 s43, s45, 0
	s_and_b64 s[40:41], s[36:37], exec
	s_cselect_b32 s41, s27, s43
	s_cselect_b32 s40, s26, s42
	s_add_u32 s38, s30, s38
	s_addc_u32 s39, s31, s39
	s_add_u32 s38, s38, 0x100
	s_addc_u32 s39, s39, 0
	s_add_i32 s72, 0, 0x10000
	s_and_b64 s[36:37], s[36:37], exec
	s_cselect_b32 s43, s25, s39
	s_cselect_b32 s42, s63, s38
	s_add_i32 s37, 0, 0x14000
	s_add_u32 s46, s44, 0x50080
	s_addc_u32 s47, s45, 0
	s_add_i32 s71, s72, s49
	s_add_i32 m0, s51, 0xc000
	s_add_i32 s74, s51, 0xe000
	s_add_i32 s68, s71, 0x2000
	s_add_u32 s44, s42, 0x10000
	s_addc_u32 s45, s43, 0
	s_add_i32 s70, s37, s49
	s_add_i32 s69, s70, 0x2000
	s_add_i32 s67, 0, 0x18000
	s_add_i32 s66, 0, 0x1c000
	s_add_u32 s38, s40, 0x50000
	s_addc_u32 s39, s41, 0
	s_add_i32 s65, s67, s49
	s_add_i32 s64, s65, 0x2000
	s_add_u32 s36, s42, 0x10080
	s_addc_u32 s37, s43, 0
	s_add_i32 s73, s66, s49
	s_add_i32 s72, s73, 0x2000
	v_lshl_add_u64 v[186:187], s[46:47], 0, v[132:133]
	global_load_lds_dwordx4 v[186:187], off
	s_mov_b32 m0, s74
	v_lshl_add_u64 v[186:187], s[46:47], 0, v[130:131]
	global_load_lds_dwordx4 v[186:187], off
	s_waitcnt vmcnt(8)
	s_waitcnt lgkmcnt(0)
	s_barrier
	s_setprio 1
	s_waitcnt lgkmcnt(0)
	v_mfma_f32_16x16x32_bf16 v[124:127], v[138:141], v[170:173], v[124:127]
	v_mfma_f32_16x16x32_bf16 v[120:123], v[146:149], v[170:173], v[120:123]
	v_mfma_f32_16x16x32_bf16 v[116:119], v[138:141], v[178:181], v[116:119]
	v_mfma_f32_16x16x32_bf16 v[112:115], v[146:149], v[178:181], v[112:115]
	v_mfma_f32_16x16x32_bf16 v[100:103], v[138:141], v[192:195], v[100:103]
	v_mfma_f32_16x16x32_bf16 v[96:99], v[146:149], v[192:195], v[96:99]
	v_mfma_f32_16x16x32_bf16 v[84:87], v[138:141], v[234:237], v[84:87]
	v_mfma_f32_16x16x32_bf16 v[80:83], v[146:149], v[234:237], v[80:83]
	v_mfma_f32_16x16x32_bf16 v[124:127], v[142:145], v[174:177], v[124:127]
	v_mfma_f32_16x16x32_bf16 v[120:123], v[150:153], v[174:177], v[120:123]
	v_mfma_f32_16x16x32_bf16 v[116:119], v[142:145], v[182:185], v[116:119]
	v_mfma_f32_16x16x32_bf16 v[112:115], v[150:153], v[182:185], v[112:115]
	v_mfma_f32_16x16x32_bf16 v[100:103], v[142:145], v[230:233], v[100:103]
	v_mfma_f32_16x16x32_bf16 v[96:99], v[150:153], v[230:233], v[96:99]
	v_mfma_f32_16x16x32_bf16 v[84:87], v[142:145], v[238:241], v[84:87]
	v_mfma_f32_16x16x32_bf16 v[80:83], v[150:153], v[238:241], v[80:83]
	s_setprio 0
	s_setprio 1
	v_mfma_f32_16x16x32_bf16 v[108:111], v[154:157], v[170:173], v[108:111]
	v_mfma_f32_16x16x32_bf16 v[104:107], v[162:165], v[170:173], v[104:107]
	v_mfma_f32_16x16x32_bf16 v[92:95], v[154:157], v[178:181], v[92:95]
	v_mfma_f32_16x16x32_bf16 v[88:91], v[162:165], v[178:181], v[88:91]
	v_mfma_f32_16x16x32_bf16 v[76:79], v[154:157], v[192:195], v[76:79]
	v_mfma_f32_16x16x32_bf16 v[72:75], v[162:165], v[192:195], v[72:75]
	v_mfma_f32_16x16x32_bf16 v[68:71], v[154:157], v[234:237], v[68:71]
	v_mfma_f32_16x16x32_bf16 v[64:67], v[162:165], v[234:237], v[64:67]
	v_mfma_f32_16x16x32_bf16 v[108:111], v[158:161], v[174:177], v[108:111]
	v_mfma_f32_16x16x32_bf16 v[104:107], v[166:169], v[174:177], v[104:107]
	v_mfma_f32_16x16x32_bf16 v[92:95], v[158:161], v[182:185], v[92:95]
	v_mfma_f32_16x16x32_bf16 v[88:91], v[166:169], v[182:185], v[88:91]
	v_mfma_f32_16x16x32_bf16 v[76:79], v[158:161], v[230:233], v[76:79]
	v_mfma_f32_16x16x32_bf16 v[72:75], v[166:169], v[230:233], v[72:75]
	v_mfma_f32_16x16x32_bf16 v[68:71], v[158:161], v[238:241], v[68:71]
	v_mfma_f32_16x16x32_bf16 v[64:67], v[166:169], v[238:241], v[64:67]
	s_setprio 0
	s_barrier
	ds_read_b128 v[170:173], v137 offset:16384
	ds_read_b128 v[174:177], v137 offset:17408
	ds_read_b128 v[178:181], v137 offset:18432
	ds_read_b128 v[182:185], v137 offset:19456
	ds_read_b128 v[192:195], v137 offset:20480
	ds_read_b128 v[230:233], v137 offset:21504
	ds_read_b128 v[234:237], v137 offset:22528
	ds_read_b128 v[238:241], v137 offset:23552
	s_mov_b32 m0, s71
	v_lshl_add_u64 v[186:187], s[42:43], 0, v[188:189]
	global_load_lds_dwordx4 v[186:187], off
	v_lshl_add_u64 v[196:197], s[42:43], 0, v[128:129]
	s_mov_b32 m0, s68
	v_lshl_add_u64 v[242:243], s[44:45], 0, v[188:189]
	global_load_lds_dwordx4 v[196:197], off
	s_waitcnt vmcnt(4)
	s_waitcnt lgkmcnt(0)
	s_barrier
; #define PG8_STAGE(bufoff, gbase, voff) do { _Pragma("unroll") for (int _i = 0; _i < 2; ++_i) \
;         __builtin_amdgcn_global_load_lds((const unsigned*)((const char*)(gbase) + (voff)[_i]), (PG8_LAS unsigned*)(lds + (bufoff) + ldsw + _i * 8192), 16, 0, 0); } while (0)
; #define PG8_LDA(dst, b, h) do { _Pragma("unroll") for (int m = 0; m < 4; ++m) _Pragma("unroll") for (int k = 0; k < 2; ++k) dst[m][k] = *(const PG8_LAS bf16x8*)(lds + PG8_SA(b, h) + aoff + m * 2048 + k * 1024); } while (0)
; #define PG8_LDB(dst, b, h) do { _Pragma("unroll") for (int n = 0; n < 2; ++n) _Pragma("unroll") for (int k = 0; k < 2; ++k) dst[n][k] = *(const PG8_LAS bf16x8*)(lds + PG8_SB(b, h) + boff + n * 2048 + k * 1024); } while (0)
; #define PG8_MMA(ai, bj, At, Bt) do { __builtin_amdgcn_s_setprio(1); _Pragma("unroll") for (int m = 0; m < 4; ++m) _Pragma("unroll") for (int n = 0; n < 2; ++n) _Pragma("unroll") for (int k = 0; k < 2; ++k) \
;         acc[ai][bj][m][n] = __builtin_amdgcn_mfma_f32_16x16x32_bf16(Bt[n][k], At[m][k], acc[ai][bj][m][n], 0, 0, 0); __builtin_amdgcn_s_setprio(0); } while (0)
; #define PG8_WAIT_V(n) asm volatile("s_waitcnt vmcnt(" #n ")" ::: "memory")
; #define PG8_WAIT_L(n) asm volatile("s_waitcnt lgkmcnt(" #n ")" ::: "memory")
; #define PG8_BAR __builtin_amdgcn_s_barrier()
; #define PG8_SCHED __builtin_amdgcn_sched_barrier(0)
; template <class Epi, class Sched, bool ALIGN_EPI = false, bool SP2 = false>
; __device__ __forceinline__ void gemm_phase(PG8_LAS unsigned char* lds, const Gemm g, const Sched& S, const Epi& E) {
;     ...
;             PG8_WAIT_V(8); PG8_WAIT_L(0); PG8_BAR; PG8_MMA(1, 0, At, B0); PG8_MMA(1, 1, At, B1); PG8_BAR; PG8_SCHED;
;             PG8_LDB(B0, 1, 0); PG8_LDB(B1, 1, 1); PG8_SCHED; PG8_LDA(At, 1, 0); PG8_STAGE(PG8_SA(0, 1), a2 + hstepA, voffA);
;             PG8_WAIT_V(8); PG8_WAIT_L(0); PG8_BAR; PG8_MMA(0, 0, At, B0); PG8_MMA(0, 1, At, B1); PG8_BAR; PG8_SCHED;
	s_setprio 1
	s_waitcnt lgkmcnt(0)
	v_mfma_f32_16x16x32_bf16 v[60:63], v[138:141], v[170:173], v[60:63]
	v_mfma_f32_16x16x32_bf16 v[56:59], v[146:149], v[170:173], v[56:59]
	s_mov_b32 m0, s70
	v_lshl_add_u64 v[244:245], s[40:41], 0, v[130:131]
	global_load_lds_dwordx4 v[242:243], off
	v_mfma_f32_16x16x32_bf16 v[52:55], v[138:141], v[178:181], v[52:55]
	v_mfma_f32_16x16x32_bf16 v[48:51], v[146:149], v[178:181], v[48:51]
	v_mfma_f32_16x16x32_bf16 v[36:39], v[138:141], v[192:195], v[36:39]
	v_mfma_f32_16x16x32_bf16 v[32:35], v[146:149], v[192:195], v[32:35]
	v_mfma_f32_16x16x32_bf16 v[20:23], v[138:141], v[234:237], v[20:23]
	v_mfma_f32_16x16x32_bf16 v[16:19], v[146:149], v[234:237], v[16:19]
	v_mfma_f32_16x16x32_bf16 v[60:63], v[142:145], v[174:177], v[60:63]
	v_mfma_f32_16x16x32_bf16 v[56:59], v[150:153], v[174:177], v[56:59]
	s_mov_b32 m0, s69
	v_lshl_add_u64 v[242:243], s[44:45], 0, v[128:129]
	global_load_lds_dwordx4 v[242:243], off
	v_mfma_f32_16x16x32_bf16 v[52:55], v[142:145], v[182:185], v[52:55]
	v_mfma_f32_16x16x32_bf16 v[48:51], v[150:153], v[182:185], v[48:51]
	v_mfma_f32_16x16x32_bf16 v[36:39], v[142:145], v[230:233], v[36:39]
	v_mfma_f32_16x16x32_bf16 v[32:35], v[150:153], v[230:233], v[32:35]
	v_mfma_f32_16x16x32_bf16 v[20:23], v[142:145], v[238:241], v[20:23]
	v_mfma_f32_16x16x32_bf16 v[16:19], v[150:153], v[238:241], v[16:19]
	s_setprio 0
	s_setprio 1
	v_mfma_f32_16x16x32_bf16 v[44:47], v[154:157], v[170:173], v[44:47]
	v_mfma_f32_16x16x32_bf16 v[40:43], v[162:165], v[170:173], v[40:43]
	s_mov_b32 m0, s51
	v_lshl_add_u64 v[242:243], s[40:41], 0, v[132:133]
	global_load_lds_dwordx4 v[242:243], off
	v_mfma_f32_16x16x32_bf16 v[28:31], v[154:157], v[178:181], v[28:31]
	v_mfma_f32_16x16x32_bf16 v[24:27], v[162:165], v[178:181], v[24:27]
	v_mfma_f32_16x16x32_bf16 v[12:15], v[154:157], v[192:195], v[12:15]
	v_mfma_f32_16x16x32_bf16 v[8:11], v[162:165], v[192:195], v[8:11]
	v_mfma_f32_16x16x32_bf16 v[4:7], v[154:157], v[234:237], v[4:7]
	v_mfma_f32_16x16x32_bf16 v[0:3], v[162:165], v[234:237], v[0:3]
	v_mfma_f32_16x16x32_bf16 v[44:47], v[158:161], v[174:177], v[44:47]
	v_mfma_f32_16x16x32_bf16 v[40:43], v[166:169], v[174:177], v[40:43]
	s_mov_b32 m0, s52
	s_nop 0
	global_load_lds_dwordx4 v[244:245], off
	v_mfma_f32_16x16x32_bf16 v[28:31], v[158:161], v[182:185], v[28:31]
	v_mfma_f32_16x16x32_bf16 v[24:27], v[166:169], v[182:185], v[24:27]
	v_mfma_f32_16x16x32_bf16 v[12:15], v[158:161], v[230:233], v[12:15]
	v_mfma_f32_16x16x32_bf16 v[8:11], v[166:169], v[230:233], v[8:11]
	v_mfma_f32_16x16x32_bf16 v[4:7], v[158:161], v[238:241], v[4:7]
	v_mfma_f32_16x16x32_bf16 v[0:3], v[166:169], v[238:241], v[0:3]
	s_setprio 0
	s_barrier
	v_add_u32_e32 v150, 0x18000, v136
	v_add_u32_e32 v166, 0x1c000, v136
	ds_read_b128 v[138:141], v150
	ds_read_b128 v[142:145], v150 offset:1024
	ds_read_b128 v[146:149], v150 offset:2048
	ds_read_b128 v[150:153], v150 offset:3072
	ds_read_b128 v[154:157], v166
	ds_read_b128 v[158:161], v166 offset:1024
	ds_read_b128 v[162:165], v166 offset:2048
	ds_read_b128 v[166:169], v166 offset:3072
	ds_read_b128 v[170:173], v137 offset:32768
	ds_read_b128 v[174:177], v137 offset:33792
	ds_read_b128 v[178:181], v137 offset:34816
	ds_read_b128 v[182:185], v137 offset:35840
	ds_read_b128 v[192:195], v137 offset:36864
	ds_read_b128 v[230:233], v137 offset:37888
	ds_read_b128 v[234:237], v137 offset:38912
	ds_read_b128 v[238:241], v137 offset:39936
	s_mov_b32 m0, s53
	v_lshl_add_u64 v[246:247], s[38:39], 0, v[132:133]
	global_load_lds_dwordx4 v[246:247], off
	s_mov_b32 m0, s54
	v_lshl_add_u64 v[246:247], s[38:39], 0, v[130:131]
	global_load_lds_dwordx4 v[246:247], off
	s_waitcnt vmcnt(8)
	s_waitcnt lgkmcnt(0)
	s_barrier
; #define PG8_STAGE(bufoff, gbase, voff) do { _Pragma("unroll") for (int _i = 0; _i < 2; ++_i) \
;         __builtin_amdgcn_global_load_lds((const unsigned*)((const char*)(gbase) + (voff)[_i]), (PG8_LAS unsigned*)(lds + (bufoff) + ldsw + _i * 8192), 16, 0, 0); } while (0)
; #define PG8_LDA(dst, b, h) do { _Pragma("unroll") for (int m = 0; m < 4; ++m) _Pragma("unroll") for (int k = 0; k < 2; ++k) dst[m][k] = *(const PG8_LAS bf16x8*)(lds + PG8_SA(b, h) + aoff + m * 2048 + k * 1024); } while (0)
; #define PG8_MMA(ai, bj, At, Bt) do { __builtin_amdgcn_s_setprio(1); _Pragma("unroll") for (int m = 0; m < 4; ++m) _Pragma("unroll") for (int n = 0; n < 2; ++n) _Pragma("unroll") for (int k = 0; k < 2; ++k) \
;         acc[ai][bj][m][n] = __builtin_amdgcn_mfma_f32_16x16x32_bf16(Bt[n][k], At[m][k], acc[ai][bj][m][n], 0, 0, 0); __builtin_amdgcn_s_setprio(0); } while (0)
; #define PG8_WAIT_V(n) asm volatile("s_waitcnt vmcnt(" #n ")" ::: "memory")
; #define PG8_WAIT_L(n) asm volatile("s_waitcnt lgkmcnt(" #n ")" ::: "memory")
; #define PG8_BAR __builtin_amdgcn_s_barrier()
; #define PG8_SCHED __builtin_amdgcn_sched_barrier(0)
; template <class Epi, class Sched, bool ALIGN_EPI = false, bool SP2 = false>
; __device__ __forceinline__ void gemm_phase(PG8_LAS unsigned char* lds, const Gemm g, const Sched& S, const Epi& E) {
;     ...
;             PG8_WAIT_V(8); PG8_WAIT_L(0); PG8_BAR; PG8_MMA(0, 0, At, B0); PG8_MMA(0, 1, At, B1); PG8_BAR; PG8_SCHED;
;             PG8_LDA(At, 1, 1); PG8_STAGE(PG8_SB(1, 0), b3, voffB); PG8_STAGE(PG8_SB(1, 1), b3 + hstepB, voffB); PG8_STAGE(PG8_SA(1, 0), a3, voffA);
;             PG8_WAIT_V(8); PG8_WAIT_L(0); PG8_BAR; PG8_MMA(1, 0, At, B0); PG8_MMA(1, 1, At, B1); PG8_BAR; PG8_SCHED;
	s_setprio 1
	s_waitcnt lgkmcnt(0)
	v_mfma_f32_16x16x32_bf16 v[124:127], v[138:141], v[170:173], v[124:127]
	v_mfma_f32_16x16x32_bf16 v[120:123], v[146:149], v[170:173], v[120:123]
	v_mfma_f32_16x16x32_bf16 v[116:119], v[138:141], v[178:181], v[116:119]
	v_mfma_f32_16x16x32_bf16 v[112:115], v[146:149], v[178:181], v[112:115]
	v_mfma_f32_16x16x32_bf16 v[100:103], v[138:141], v[192:195], v[100:103]
	v_mfma_f32_16x16x32_bf16 v[96:99], v[146:149], v[192:195], v[96:99]
	v_mfma_f32_16x16x32_bf16 v[84:87], v[138:141], v[234:237], v[84:87]
	v_mfma_f32_16x16x32_bf16 v[80:83], v[146:149], v[234:237], v[80:83]
	v_mfma_f32_16x16x32_bf16 v[124:127], v[142:145], v[174:177], v[124:127]
	v_mfma_f32_16x16x32_bf16 v[120:123], v[150:153], v[174:177], v[120:123]
	v_mfma_f32_16x16x32_bf16 v[116:119], v[142:145], v[182:185], v[116:119]
	v_mfma_f32_16x16x32_bf16 v[112:115], v[150:153], v[182:185], v[112:115]
	v_mfma_f32_16x16x32_bf16 v[100:103], v[142:145], v[230:233], v[100:103]
	v_mfma_f32_16x16x32_bf16 v[96:99], v[150:153], v[230:233], v[96:99]
	v_mfma_f32_16x16x32_bf16 v[84:87], v[142:145], v[238:241], v[84:87]
	v_mfma_f32_16x16x32_bf16 v[80:83], v[150:153], v[238:241], v[80:83]
	s_setprio 0
	s_setprio 1
	v_mfma_f32_16x16x32_bf16 v[108:111], v[154:157], v[170:173], v[108:111]
	v_mfma_f32_16x16x32_bf16 v[104:107], v[162:165], v[170:173], v[104:107]
	v_mfma_f32_16x16x32_bf16 v[92:95], v[154:157], v[178:181], v[92:95]
	v_mfma_f32_16x16x32_bf16 v[88:91], v[162:165], v[178:181], v[88:91]
	v_mfma_f32_16x16x32_bf16 v[76:79], v[154:157], v[192:195], v[76:79]
	v_mfma_f32_16x16x32_bf16 v[72:75], v[162:165], v[192:195], v[72:75]
	v_mfma_f32_16x16x32_bf16 v[68:71], v[154:157], v[234:237], v[68:71]
	v_mfma_f32_16x16x32_bf16 v[64:67], v[162:165], v[234:237], v[64:67]
	v_mfma_f32_16x16x32_bf16 v[108:111], v[158:161], v[174:177], v[108:111]
	v_mfma_f32_16x16x32_bf16 v[104:107], v[166:169], v[174:177], v[104:107]
	v_mfma_f32_16x16x32_bf16 v[92:95], v[158:161], v[182:185], v[92:95]
	v_mfma_f32_16x16x32_bf16 v[88:91], v[166:169], v[182:185], v[88:91]
	v_mfma_f32_16x16x32_bf16 v[76:79], v[158:161], v[230:233], v[76:79]
	v_mfma_f32_16x16x32_bf16 v[72:75], v[166:169], v[230:233], v[72:75]
	v_mfma_f32_16x16x32_bf16 v[68:71], v[158:161], v[238:241], v[68:71]
	v_mfma_f32_16x16x32_bf16 v[64:67], v[166:169], v[238:241], v[64:67]
	s_setprio 0
	s_barrier
	ds_read_b128 v[170:173], v137 offset:49152
	ds_read_b128 v[174:177], v137 offset:50176
	ds_read_b128 v[178:181], v137 offset:51200
	ds_read_b128 v[182:185], v137 offset:52224
	ds_read_b128 v[192:195], v137 offset:53248
	ds_read_b128 v[230:233], v137 offset:54272
	ds_read_b128 v[234:237], v137 offset:55296
	ds_read_b128 v[238:241], v137 offset:56320
	s_mov_b32 m0, s65
	v_lshl_add_u64 v[186:187], v[186:187], 0, s[94:95]
	global_load_lds_dwordx4 v[186:187], off
	s_mov_b32 m0, s64
	v_lshl_add_u64 v[186:187], v[196:197], 0, s[94:95]
	global_load_lds_dwordx4 v[186:187], off
	s_waitcnt vmcnt(4)
	s_waitcnt lgkmcnt(0)
	s_barrier
	s_setprio 1
	s_waitcnt lgkmcnt(0)
	v_mfma_f32_16x16x32_bf16 v[60:63], v[138:141], v[170:173], v[60:63]
	v_mfma_f32_16x16x32_bf16 v[56:59], v[146:149], v[170:173], v[56:59]
	s_mov_b32 m0, s73
	v_lshl_add_u64 v[186:187], s[36:37], 0, v[188:189]
	global_load_lds_dwordx4 v[186:187], off
	v_mfma_f32_16x16x32_bf16 v[52:55], v[138:141], v[178:181], v[52:55]
	v_mfma_f32_16x16x32_bf16 v[48:51], v[146:149], v[178:181], v[48:51]
	v_mfma_f32_16x16x32_bf16 v[36:39], v[138:141], v[192:195], v[36:39]
	v_mfma_f32_16x16x32_bf16 v[32:35], v[146:149], v[192:195], v[32:35]
	v_mfma_f32_16x16x32_bf16 v[20:23], v[138:141], v[234:237], v[20:23]
	v_mfma_f32_16x16x32_bf16 v[16:19], v[146:149], v[234:237], v[16:19]
	v_mfma_f32_16x16x32_bf16 v[60:63], v[142:145], v[174:177], v[60:63]
	v_mfma_f32_16x16x32_bf16 v[56:59], v[150:153], v[174:177], v[56:59]
	s_mov_b32 m0, s72
	v_lshl_add_u64 v[186:187], s[36:37], 0, v[128:129]
	global_load_lds_dwordx4 v[186:187], off
	v_mfma_f32_16x16x32_bf16 v[52:55], v[142:145], v[182:185], v[52:55]
	v_mfma_f32_16x16x32_bf16 v[48:51], v[150:153], v[182:185], v[48:51]
	v_mfma_f32_16x16x32_bf16 v[36:39], v[142:145], v[230:233], v[36:39]
	v_mfma_f32_16x16x32_bf16 v[32:35], v[150:153], v[230:233], v[32:35]
	v_mfma_f32_16x16x32_bf16 v[20:23], v[142:145], v[238:241], v[20:23]
	v_mfma_f32_16x16x32_bf16 v[16:19], v[150:153], v[238:241], v[16:19]
	s_setprio 0
	s_setprio 1
	v_mfma_f32_16x16x32_bf16 v[44:47], v[154:157], v[170:173], v[44:47]
	v_mfma_f32_16x16x32_bf16 v[40:43], v[162:165], v[170:173], v[40:43]
	s_mov_b32 m0, s56
	v_lshl_add_u64 v[186:187], v[242:243], 0, s[94:95]
	global_load_lds_dwordx4 v[186:187], off
	v_mfma_f32_16x16x32_bf16 v[28:31], v[154:157], v[178:181], v[28:31]
	v_mfma_f32_16x16x32_bf16 v[24:27], v[162:165], v[178:181], v[24:27]
	v_mfma_f32_16x16x32_bf16 v[12:15], v[154:157], v[192:195], v[12:15]
	v_mfma_f32_16x16x32_bf16 v[8:11], v[162:165], v[192:195], v[8:11]
	v_mfma_f32_16x16x32_bf16 v[4:7], v[154:157], v[234:237], v[4:7]
	v_mfma_f32_16x16x32_bf16 v[0:3], v[162:165], v[234:237], v[0:3]
	v_mfma_f32_16x16x32_bf16 v[44:47], v[158:161], v[174:177], v[44:47]
	v_mfma_f32_16x16x32_bf16 v[40:43], v[166:169], v[174:177], v[40:43]
	s_mov_b32 m0, s57
	v_lshl_add_u64 v[186:187], v[244:245], 0, s[94:95]
	global_load_lds_dwordx4 v[186:187], off
	v_mfma_f32_16x16x32_bf16 v[28:31], v[158:161], v[182:185], v[28:31]
	v_mfma_f32_16x16x32_bf16 v[24:27], v[166:169], v[182:185], v[24:27]
	v_mfma_f32_16x16x32_bf16 v[12:15], v[158:161], v[230:233], v[12:15]
	v_mfma_f32_16x16x32_bf16 v[8:11], v[166:169], v[230:233], v[8:11]
	v_mfma_f32_16x16x32_bf16 v[4:7], v[158:161], v[238:241], v[4:7]
	v_mfma_f32_16x16x32_bf16 v[0:3], v[166:169], v[238:241], v[0:3]
	s_setprio 0
	s_barrier
	s_andn2_b64 vcc, exec, s[8:9]
	s_mov_b64 s[36:37], -1
	s_mov_b64 s[8:9], 0
	s_mov_b64 s[38:39], 0x100
	s_cbranch_vccz .LBB0_901
	s_and_b64 vcc, exec, s[20:21]
	s_cbranch_vccz .LBB0_904
	s_barrier

; #define PG8_STAGE(bufoff, gbase, voff) do { _Pragma("unroll") for (int _i = 0; _i < 2; ++_i) \
;         __builtin_amdgcn_global_load_lds((const unsigned*)((const char*)(gbase) + (voff)[_i]), (PG8_LAS unsigned*)(lds + (bufoff) + ldsw + _i * 8192), 16, 0, 0); } while (0)
; #define PG8_LDA(dst, b, h) do { _Pragma("unroll") for (int m = 0; m < 4; ++m) _Pragma("unroll") for (int k = 0; k < 2; ++k) dst[m][k] = *(const PG8_LAS bf16x8*)(lds + PG8_SA(b, h) + aoff + m * 2048 + k * 1024); } while (0)
; #define PG8_LDB(dst, b, h) do { _Pragma("unroll") for (int n = 0; n < 2; ++n) _Pragma("unroll") for (int k = 0; k < 2; ++k) dst[n][k] = *(const PG8_LAS bf16x8*)(lds + PG8_SB(b, h) + boff + n * 2048 + k * 1024); } while (0)
; #define PG8_MMA(ai, bj, At, Bt) do { __builtin_amdgcn_s_setprio(1); _Pragma("unroll") for (int m = 0; m < 4; ++m) _Pragma("unroll") for (int n = 0; n < 2; ++n) _Pragma("unroll") for (int k = 0; k < 2; ++k) \
;         acc[ai][bj][m][n] = __builtin_amdgcn_mfma_f32_16x16x32_bf16(Bt[n][k], At[m][k], acc[ai][bj][m][n], 0, 0, 0); __builtin_amdgcn_s_setprio(0); } while (0)
; #define PG8_WAIT_V(n) asm volatile("s_waitcnt vmcnt(" #n ")" ::: "memory")
; #define PG8_WAIT_L(n) asm volatile("s_waitcnt lgkmcnt(" #n ")" ::: "memory")
; template <class Epi, class Sched, bool ALIGN_EPI = false, bool SP2 = false>
; __device__ __forceinline__ void gemm_phase(PG8_LAS unsigned char* lds, const Gemm g, const Sched& S, const Epi& E) {
;     ...
;             const bool last = (t == nt - 2);
;             const char* a1 = cA + (size_t)(t + 1) * kstep;
;             const char* a2 = last ? nA : cA + (size_t)(t + 2) * kstep; const char* b2 = last ? nB : cB + (size_t)(t + 2) * kstep;
;             const char* a3 = a2 + kstep; const char* b3 = b2 + kstep;
;             if (last && has_next) S.a_ready(nxt);
;             if constexpr (SP2) {
;             PG8_LDB(B0, 0, 0); PG8_LDB(B1, 0, 1); PG8_SCHED; PG8_LDA(At, 0, 0); PG8_STAGE(PG8_SA(1, 1), a1 + hstepA, voffA);
;             PG8_WAIT_V(8); PG8_WAIT_L(0); PG8_BAR; PG8_MMA(0, 0, At, B0); PG8_MMA(0, 1, At, B1); PG8_BAR; PG8_SCHED;
;             PG8_LDA(At, 0, 1); PG8_STAGE(PG8_SB(0, 0), b2, voffB); PG8_STAGE(PG8_SB(0, 1), b2 + hstepB, voffB); PG8_STAGE(PG8_SA(0, 0), a2, voffA);
;             PG8_WAIT_V(8); PG8_WAIT_L(0); PG8_BAR; PG8_MMA(1, 0, At, B0); PG8_MMA(1, 1, At, B1); PG8_BAR; PG8_SCHED;
.LBB0_1642:
	v_add_u32_e32 v150, 0x10000, v148
	v_add_u32_e32 v166, 0x14000, v148
	ds_read_b128 v[128:131], v150
	ds_read_b128 v[138:141], v150 offset:1024
	ds_read_b128 v[142:145], v150 offset:2048
	ds_read_b128 v[150:153], v150 offset:3072
	ds_read_b128 v[154:157], v166
	ds_read_b128 v[158:161], v166 offset:1024
	ds_read_b128 v[162:165], v166 offset:2048
	ds_read_b128 v[166:169], v166 offset:3072
	ds_read_b128 v[170:173], v149
	ds_read_b128 v[174:177], v149 offset:1024
	ds_read_b128 v[178:181], v149 offset:2048
	ds_read_b128 v[182:185], v149 offset:3072
	ds_read_b128 v[192:195], v149 offset:4096
	ds_read_b128 v[230:233], v149 offset:5120
	ds_read_b128 v[234:237], v149 offset:6144
	ds_read_b128 v[238:241], v149 offset:7168
	s_add_i32 s74, s28, 2
	s_add_u32 s75, s26, 0x80
	s_addc_u32 s29, s27, 0
	s_add_i32 s78, 0, 0x10000
	s_cmp_eq_u32 s54, s28
	s_cselect_b32 s29, s9, s29
	s_cselect_b32 s28, s8, s75
	s_cselect_b32 s77, s25, s73
	s_cselect_b32 s76, s24, s72
	s_add_i32 s75, 0, 0x14000
	s_add_i32 m0, s36, 0xc000
	v_lshl_add_u64 v[186:187], s[26:27], 0, v[134:135]
	global_load_lds_dwordx4 v[186:187], off
	s_add_i32 m0, s36, 0xe000
	v_lshl_add_u64 v[186:187], s[26:27], 0, v[136:137]
	global_load_lds_dwordx4 v[186:187], off
	s_waitcnt vmcnt(8)
	s_waitcnt lgkmcnt(0)
	s_barrier
	s_setprio 1
	s_waitcnt lgkmcnt(0)
	v_mfma_f32_16x16x32_bf16 v[124:127], v[128:131], v[170:173], v[124:127]
	v_mfma_f32_16x16x32_bf16 v[96:99], v[142:145], v[170:173], v[96:99]
	v_mfma_f32_16x16x32_bf16 v[120:123], v[128:131], v[178:181], v[120:123]
	v_mfma_f32_16x16x32_bf16 v[92:95], v[142:145], v[178:181], v[92:95]
	v_mfma_f32_16x16x32_bf16 v[116:119], v[128:131], v[192:195], v[116:119]
	v_mfma_f32_16x16x32_bf16 v[88:91], v[142:145], v[192:195], v[88:91]
	v_mfma_f32_16x16x32_bf16 v[112:115], v[128:131], v[234:237], v[112:115]
	v_mfma_f32_16x16x32_bf16 v[80:83], v[142:145], v[234:237], v[80:83]
	v_mfma_f32_16x16x32_bf16 v[124:127], v[138:141], v[174:177], v[124:127]
	v_mfma_f32_16x16x32_bf16 v[96:99], v[150:153], v[174:177], v[96:99]
	v_mfma_f32_16x16x32_bf16 v[120:123], v[138:141], v[182:185], v[120:123]
	v_mfma_f32_16x16x32_bf16 v[92:95], v[150:153], v[182:185], v[92:95]
	v_mfma_f32_16x16x32_bf16 v[116:119], v[138:141], v[230:233], v[116:119]
	v_mfma_f32_16x16x32_bf16 v[88:91], v[150:153], v[230:233], v[88:91]
	v_mfma_f32_16x16x32_bf16 v[112:115], v[138:141], v[238:241], v[112:115]
	v_mfma_f32_16x16x32_bf16 v[80:83], v[150:153], v[238:241], v[80:83]
	s_setprio 0
	s_setprio 1
	v_mfma_f32_16x16x32_bf16 v[72:75], v[154:157], v[170:173], v[72:75]
	v_mfma_f32_16x16x32_bf16 v[44:47], v[162:165], v[170:173], v[44:47]
	v_mfma_f32_16x16x32_bf16 v[64:67], v[154:157], v[178:181], v[64:67]
	v_mfma_f32_16x16x32_bf16 v[36:39], v[162:165], v[178:181], v[36:39]
	v_mfma_f32_16x16x32_bf16 v[56:59], v[154:157], v[192:195], v[56:59]
	v_mfma_f32_16x16x32_bf16 v[28:31], v[162:165], v[192:195], v[28:31]
	v_mfma_f32_16x16x32_bf16 v[48:51], v[154:157], v[234:237], v[48:51]
	v_mfma_f32_16x16x32_bf16 v[20:23], v[162:165], v[234:237], v[20:23]
	v_mfma_f32_16x16x32_bf16 v[72:75], v[158:161], v[174:177], v[72:75]
	v_mfma_f32_16x16x32_bf16 v[44:47], v[166:169], v[174:177], v[44:47]
	v_mfma_f32_16x16x32_bf16 v[64:67], v[158:161], v[182:185], v[64:67]
	v_mfma_f32_16x16x32_bf16 v[36:39], v[166:169], v[182:185], v[36:39]
	v_mfma_f32_16x16x32_bf16 v[56:59], v[158:161], v[230:233], v[56:59]
	v_mfma_f32_16x16x32_bf16 v[28:31], v[166:169], v[230:233], v[28:31]
	v_mfma_f32_16x16x32_bf16 v[48:51], v[158:161], v[238:241], v[48:51]
	v_mfma_f32_16x16x32_bf16 v[20:23], v[166:169], v[238:241], v[20:23]
	s_setprio 0
	s_barrier
	ds_read_b128 v[170:173], v149 offset:16384
	ds_read_b128 v[174:177], v149 offset:17408
	ds_read_b128 v[178:181], v149 offset:18432
	ds_read_b128 v[182:185], v149 offset:19456
	ds_read_b128 v[192:195], v149 offset:20480
	ds_read_b128 v[230:233], v149 offset:21504
	ds_read_b128 v[234:237], v149 offset:22528
	ds_read_b128 v[238:241], v149 offset:23552
	s_add_i32 s78, s78, s30
	s_mov_b32 m0, s78
	v_lshl_add_u64 v[186:187], s[76:77], 0, v[188:189]
	global_load_lds_dwordx4 v[186:187], off
	s_add_i32 m0, s78, 0x2000
	v_lshl_add_u64 v[196:197], s[76:77], 0, v[132:133]
	s_add_u32 s76, s76, s44
	s_addc_u32 s77, s77, 0
	s_add_i32 s75, s75, s30
	global_load_lds_dwordx4 v[196:197], off
	s_waitcnt vmcnt(4)
	s_waitcnt lgkmcnt(0)
	s_barrier
; #define PG8_STAGE(bufoff, gbase, voff) do { _Pragma("unroll") for (int _i = 0; _i < 2; ++_i) \
;         __builtin_amdgcn_global_load_lds((const unsigned*)((const char*)(gbase) + (voff)[_i]), (PG8_LAS unsigned*)(lds + (bufoff) + ldsw + _i * 8192), 16, 0, 0); } while (0)
; #define PG8_LDA(dst, b, h) do { _Pragma("unroll") for (int m = 0; m < 4; ++m) _Pragma("unroll") for (int k = 0; k < 2; ++k) dst[m][k] = *(const PG8_LAS bf16x8*)(lds + PG8_SA(b, h) + aoff + m * 2048 + k * 1024); } while (0)
; #define PG8_LDB(dst, b, h) do { _Pragma("unroll") for (int n = 0; n < 2; ++n) _Pragma("unroll") for (int k = 0; k < 2; ++k) dst[n][k] = *(const PG8_LAS bf16x8*)(lds + PG8_SB(b, h) + boff + n * 2048 + k * 1024); } while (0)
; #define PG8_MMA(ai, bj, At, Bt) do { __builtin_amdgcn_s_setprio(1); _Pragma("unroll") for (int m = 0; m < 4; ++m) _Pragma("unroll") for (int n = 0; n < 2; ++n) _Pragma("unroll") for (int k = 0; k < 2; ++k) \
;         acc[ai][bj][m][n] = __builtin_amdgcn_mfma_f32_16x16x32_bf16(Bt[n][k], At[m][k], acc[ai][bj][m][n], 0, 0, 0); __builtin_amdgcn_s_setprio(0); } while (0)
; #define PG8_WAIT_V(n) asm volatile("s_waitcnt vmcnt(" #n ")" ::: "memory")
; #define PG8_WAIT_L(n) asm volatile("s_waitcnt lgkmcnt(" #n ")" ::: "memory")
; #define PG8_BAR __builtin_amdgcn_s_barrier()
; #define PG8_SCHED __builtin_amdgcn_sched_barrier(0)
; template <class Epi, class Sched, bool ALIGN_EPI = false, bool SP2 = false>
; __device__ __forceinline__ void gemm_phase(PG8_LAS unsigned char* lds, const Gemm g, const Sched& S, const Epi& E) {
;     ...
;             PG8_WAIT_V(8); PG8_WAIT_L(0); PG8_BAR; PG8_MMA(1, 0, At, B0); PG8_MMA(1, 1, At, B1); PG8_BAR; PG8_SCHED;
;             PG8_LDB(B0, 1, 0); PG8_LDB(B1, 1, 1); PG8_SCHED; PG8_LDA(At, 1, 0); PG8_STAGE(PG8_SA(0, 1), a2 + hstepA, voffA);
;             PG8_WAIT_V(8); PG8_WAIT_L(0); PG8_BAR; PG8_MMA(0, 0, At, B0); PG8_MMA(0, 1, At, B1); PG8_BAR; PG8_SCHED;
	s_setprio 1
	s_waitcnt lgkmcnt(0)
	v_mfma_f32_16x16x32_bf16 v[108:111], v[128:131], v[170:173], v[108:111]
	v_mfma_f32_16x16x32_bf16 v[76:79], v[142:145], v[170:173], v[76:79]
	v_lshl_add_u64 v[242:243], s[76:77], 0, v[188:189]
	s_mov_b32 m0, s75
	v_lshl_add_u64 v[244:245], s[76:77], 0, v[132:133]
	global_load_lds_dwordx4 v[242:243], off
	v_mfma_f32_16x16x32_bf16 v[104:107], v[128:131], v[178:181], v[104:107]
	v_mfma_f32_16x16x32_bf16 v[68:71], v[142:145], v[178:181], v[68:71]
	v_mfma_f32_16x16x32_bf16 v[100:103], v[128:131], v[192:195], v[100:103]
	v_mfma_f32_16x16x32_bf16 v[60:63], v[142:145], v[192:195], v[60:63]
	v_mfma_f32_16x16x32_bf16 v[84:87], v[128:131], v[234:237], v[84:87]
	v_mfma_f32_16x16x32_bf16 v[52:55], v[142:145], v[234:237], v[52:55]
	v_mfma_f32_16x16x32_bf16 v[108:111], v[138:141], v[174:177], v[108:111]
	v_mfma_f32_16x16x32_bf16 v[76:79], v[150:153], v[174:177], v[76:79]
	s_add_i32 m0, s75, 0x2000
	v_lshl_add_u64 v[246:247], s[28:29], 0, v[188:189]
	global_load_lds_dwordx4 v[244:245], off
	v_mfma_f32_16x16x32_bf16 v[104:107], v[138:141], v[182:185], v[104:107]
	v_mfma_f32_16x16x32_bf16 v[68:71], v[150:153], v[182:185], v[68:71]
	v_mfma_f32_16x16x32_bf16 v[100:103], v[138:141], v[230:233], v[100:103]
	v_mfma_f32_16x16x32_bf16 v[60:63], v[150:153], v[230:233], v[60:63]
	v_mfma_f32_16x16x32_bf16 v[84:87], v[138:141], v[238:241], v[84:87]
	v_mfma_f32_16x16x32_bf16 v[52:55], v[150:153], v[238:241], v[52:55]
	s_setprio 0
	s_setprio 1
	v_mfma_f32_16x16x32_bf16 v[40:43], v[154:157], v[170:173], v[40:43]
	v_mfma_f32_16x16x32_bf16 v[12:15], v[162:165], v[170:173], v[12:15]
	s_mov_b32 m0, s36
	v_lshl_add_u64 v[248:249], s[28:29], 0, v[132:133]
	global_load_lds_dwordx4 v[246:247], off
	v_mfma_f32_16x16x32_bf16 v[32:35], v[154:157], v[178:181], v[32:35]
	v_mfma_f32_16x16x32_bf16 v[8:11], v[162:165], v[178:181], v[8:11]
	v_mfma_f32_16x16x32_bf16 v[24:27], v[154:157], v[192:195], v[24:27]
	v_mfma_f32_16x16x32_bf16 v[4:7], v[162:165], v[192:195], v[4:7]
	v_mfma_f32_16x16x32_bf16 v[16:19], v[154:157], v[234:237], v[16:19]
	v_mfma_f32_16x16x32_bf16 v[0:3], v[162:165], v[234:237], v[0:3]
	v_mfma_f32_16x16x32_bf16 v[40:43], v[158:161], v[174:177], v[40:43]
	v_mfma_f32_16x16x32_bf16 v[12:15], v[166:169], v[174:177], v[12:15]
	s_mov_b32 m0, s37
	s_nop 0
	global_load_lds_dwordx4 v[248:249], off
	v_mfma_f32_16x16x32_bf16 v[32:35], v[158:161], v[182:185], v[32:35]
	v_mfma_f32_16x16x32_bf16 v[8:11], v[166:169], v[182:185], v[8:11]
	v_mfma_f32_16x16x32_bf16 v[24:27], v[158:161], v[230:233], v[24:27]
	v_mfma_f32_16x16x32_bf16 v[4:7], v[166:169], v[230:233], v[4:7]
	v_mfma_f32_16x16x32_bf16 v[16:19], v[158:161], v[238:241], v[16:19]
	v_mfma_f32_16x16x32_bf16 v[0:3], v[166:169], v[238:241], v[0:3]
	s_setprio 0
	s_barrier
	v_add_u32_e32 v150, 0x18000, v148
	v_add_u32_e32 v166, 0x1c000, v148
	ds_read_b128 v[128:131], v150
	ds_read_b128 v[138:141], v150 offset:1024
	ds_read_b128 v[142:145], v150 offset:2048
	ds_read_b128 v[150:153], v150 offset:3072
	ds_read_b128 v[154:157], v166
	ds_read_b128 v[158:161], v166 offset:1024
	ds_read_b128 v[162:165], v166 offset:2048
	ds_read_b128 v[166:169], v166 offset:3072
	ds_read_b128 v[170:173], v149 offset:32768
	ds_read_b128 v[174:177], v149 offset:33792
	ds_read_b128 v[178:181], v149 offset:34816
	ds_read_b128 v[182:185], v149 offset:35840
	ds_read_b128 v[192:195], v149 offset:36864
	ds_read_b128 v[230:233], v149 offset:37888
	ds_read_b128 v[234:237], v149 offset:38912
	ds_read_b128 v[238:241], v149 offset:39936
	s_add_i32 s75, 0, 0x18000
	s_add_i32 s76, 0, 0x1c000
	s_add_u32 s28, s28, s44
	s_addc_u32 s29, s29, 0
	s_mov_b32 m0, s46
	v_lshl_add_u64 v[250:251], s[28:29], 0, v[188:189]
	global_load_lds_dwordx4 v[250:251], off
	s_mov_b32 m0, s47
	v_lshl_add_u64 v[250:251], s[28:29], 0, v[132:133]
	global_load_lds_dwordx4 v[250:251], off
	s_waitcnt vmcnt(8)
	s_waitcnt lgkmcnt(0)
	s_barrier
; #define PG8_STAGE(bufoff, gbase, voff) do { _Pragma("unroll") for (int _i = 0; _i < 2; ++_i) \
;         __builtin_amdgcn_global_load_lds((const unsigned*)((const char*)(gbase) + (voff)[_i]), (PG8_LAS unsigned*)(lds + (bufoff) + ldsw + _i * 8192), 16, 0, 0); } while (0)
; #define PG8_LDA(dst, b, h) do { _Pragma("unroll") for (int m = 0; m < 4; ++m) _Pragma("unroll") for (int k = 0; k < 2; ++k) dst[m][k] = *(const PG8_LAS bf16x8*)(lds + PG8_SA(b, h) + aoff + m * 2048 + k * 1024); } while (0)
; #define PG8_MMA(ai, bj, At, Bt) do { __builtin_amdgcn_s_setprio(1); _Pragma("unroll") for (int m = 0; m < 4; ++m) _Pragma("unroll") for (int n = 0; n < 2; ++n) _Pragma("unroll") for (int k = 0; k < 2; ++k) \
;         acc[ai][bj][m][n] = __builtin_amdgcn_mfma_f32_16x16x32_bf16(Bt[n][k], At[m][k], acc[ai][bj][m][n], 0, 0, 0); __builtin_amdgcn_s_setprio(0); } while (0)
; #define PG8_WAIT_V(n) asm volatile("s_waitcnt vmcnt(" #n ")" ::: "memory")
; #define PG8_WAIT_L(n) asm volatile("s_waitcnt lgkmcnt(" #n ")" ::: "memory")
; #define PG8_BAR __builtin_amdgcn_s_barrier()
; #define PG8_SCHED __builtin_amdgcn_sched_barrier(0)
; template <class Epi, class Sched, bool ALIGN_EPI = false, bool SP2 = false>
; __device__ __forceinline__ void gemm_phase(PG8_LAS unsigned char* lds, const Gemm g, const Sched& S, const Epi& E) {
;     ...
;         for (int t = 0; t < nt; t += 2) {
;     ...
;             PG8_WAIT_V(8); PG8_WAIT_L(0); PG8_BAR; PG8_MMA(0, 0, At, B0); PG8_MMA(0, 1, At, B1); PG8_BAR; PG8_SCHED;
;             PG8_LDA(At, 1, 1); PG8_STAGE(PG8_SB(1, 0), b3, voffB); PG8_STAGE(PG8_SB(1, 1), b3 + hstepB, voffB); PG8_STAGE(PG8_SA(1, 0), a3, voffA);
;             PG8_WAIT_V(8); PG8_WAIT_L(0); PG8_BAR; PG8_MMA(1, 0, At, B0); PG8_MMA(1, 1, At, B1); PG8_BAR; PG8_SCHED;
	s_setprio 1
	s_waitcnt lgkmcnt(0)
	v_mfma_f32_16x16x32_bf16 v[124:127], v[128:131], v[170:173], v[124:127]
	v_mfma_f32_16x16x32_bf16 v[96:99], v[142:145], v[170:173], v[96:99]
	v_mfma_f32_16x16x32_bf16 v[120:123], v[128:131], v[178:181], v[120:123]
	v_mfma_f32_16x16x32_bf16 v[92:95], v[142:145], v[178:181], v[92:95]
	v_mfma_f32_16x16x32_bf16 v[116:119], v[128:131], v[192:195], v[116:119]
	v_mfma_f32_16x16x32_bf16 v[88:91], v[142:145], v[192:195], v[88:91]
	v_mfma_f32_16x16x32_bf16 v[112:115], v[128:131], v[234:237], v[112:115]
	v_mfma_f32_16x16x32_bf16 v[80:83], v[142:145], v[234:237], v[80:83]
	v_mfma_f32_16x16x32_bf16 v[124:127], v[138:141], v[174:177], v[124:127]
	v_mfma_f32_16x16x32_bf16 v[96:99], v[150:153], v[174:177], v[96:99]
	v_mfma_f32_16x16x32_bf16 v[120:123], v[138:141], v[182:185], v[120:123]
	v_mfma_f32_16x16x32_bf16 v[92:95], v[150:153], v[182:185], v[92:95]
	v_mfma_f32_16x16x32_bf16 v[116:119], v[138:141], v[230:233], v[116:119]
	v_mfma_f32_16x16x32_bf16 v[88:91], v[150:153], v[230:233], v[88:91]
	v_mfma_f32_16x16x32_bf16 v[112:115], v[138:141], v[238:241], v[112:115]
	v_mfma_f32_16x16x32_bf16 v[80:83], v[150:153], v[238:241], v[80:83]
	s_setprio 0
	s_setprio 1
	v_mfma_f32_16x16x32_bf16 v[72:75], v[154:157], v[170:173], v[72:75]
	v_mfma_f32_16x16x32_bf16 v[44:47], v[162:165], v[170:173], v[44:47]
	v_mfma_f32_16x16x32_bf16 v[64:67], v[154:157], v[178:181], v[64:67]
	v_mfma_f32_16x16x32_bf16 v[36:39], v[162:165], v[178:181], v[36:39]
	v_mfma_f32_16x16x32_bf16 v[56:59], v[154:157], v[192:195], v[56:59]
	v_mfma_f32_16x16x32_bf16 v[28:31], v[162:165], v[192:195], v[28:31]
	v_mfma_f32_16x16x32_bf16 v[48:51], v[154:157], v[234:237], v[48:51]
	v_mfma_f32_16x16x32_bf16 v[20:23], v[162:165], v[234:237], v[20:23]
	v_mfma_f32_16x16x32_bf16 v[72:75], v[158:161], v[174:177], v[72:75]
	v_mfma_f32_16x16x32_bf16 v[44:47], v[166:169], v[174:177], v[44:47]
	v_mfma_f32_16x16x32_bf16 v[64:67], v[158:161], v[182:185], v[64:67]
	v_mfma_f32_16x16x32_bf16 v[36:39], v[166:169], v[182:185], v[36:39]
	v_mfma_f32_16x16x32_bf16 v[56:59], v[158:161], v[230:233], v[56:59]
	v_mfma_f32_16x16x32_bf16 v[28:31], v[166:169], v[230:233], v[28:31]
	v_mfma_f32_16x16x32_bf16 v[48:51], v[158:161], v[238:241], v[48:51]
	v_mfma_f32_16x16x32_bf16 v[20:23], v[166:169], v[238:241], v[20:23]
	s_setprio 0
	s_barrier
	ds_read_b128 v[170:173], v149 offset:49152
	ds_read_b128 v[174:177], v149 offset:50176
	ds_read_b128 v[178:181], v149 offset:51200
	ds_read_b128 v[182:185], v149 offset:52224
	ds_read_b128 v[192:195], v149 offset:53248
	ds_read_b128 v[230:233], v149 offset:54272
	ds_read_b128 v[234:237], v149 offset:55296
	ds_read_b128 v[238:241], v149 offset:56320
	s_add_i32 s28, s75, s30
	s_mov_b32 m0, s28
	v_lshl_add_u64 v[186:187], v[186:187], 0, s[94:95]
	global_load_lds_dwordx4 v[186:187], off
	v_lshl_add_u64 v[186:187], v[196:197], 0, s[94:95]
	s_add_i32 m0, s28, 0x2000
	s_add_i32 s28, s76, s30
	global_load_lds_dwordx4 v[186:187], off
	s_waitcnt vmcnt(4)
	s_waitcnt lgkmcnt(0)
	s_barrier
	s_setprio 1
	s_waitcnt lgkmcnt(0)
	v_mfma_f32_16x16x32_bf16 v[108:111], v[128:131], v[170:173], v[108:111]
	v_mfma_f32_16x16x32_bf16 v[76:79], v[142:145], v[170:173], v[76:79]
	s_mov_b32 m0, s28
	v_lshl_add_u64 v[186:187], v[242:243], 0, s[94:95]
	global_load_lds_dwordx4 v[186:187], off
	v_mfma_f32_16x16x32_bf16 v[104:107], v[128:131], v[178:181], v[104:107]
	v_mfma_f32_16x16x32_bf16 v[68:71], v[142:145], v[178:181], v[68:71]
	v_mfma_f32_16x16x32_bf16 v[100:103], v[128:131], v[192:195], v[100:103]
	v_mfma_f32_16x16x32_bf16 v[60:63], v[142:145], v[192:195], v[60:63]
	v_mfma_f32_16x16x32_bf16 v[84:87], v[128:131], v[234:237], v[84:87]
	v_mfma_f32_16x16x32_bf16 v[52:55], v[142:145], v[234:237], v[52:55]
	v_mfma_f32_16x16x32_bf16 v[108:111], v[138:141], v[174:177], v[108:111]
	v_mfma_f32_16x16x32_bf16 v[76:79], v[150:153], v[174:177], v[76:79]
	s_add_i32 m0, s28, 0x2000
	v_lshl_add_u64 v[186:187], v[244:245], 0, s[94:95]
	global_load_lds_dwordx4 v[186:187], off
	v_mfma_f32_16x16x32_bf16 v[104:107], v[138:141], v[182:185], v[104:107]
	v_mfma_f32_16x16x32_bf16 v[68:71], v[150:153], v[182:185], v[68:71]
	v_mfma_f32_16x16x32_bf16 v[100:103], v[138:141], v[230:233], v[100:103]
	v_mfma_f32_16x16x32_bf16 v[60:63], v[150:153], v[230:233], v[60:63]
	v_mfma_f32_16x16x32_bf16 v[84:87], v[138:141], v[238:241], v[84:87]
	v_mfma_f32_16x16x32_bf16 v[52:55], v[150:153], v[238:241], v[52:55]
	s_setprio 0
	s_setprio 1
	v_mfma_f32_16x16x32_bf16 v[40:43], v[154:157], v[170:173], v[40:43]
	v_mfma_f32_16x16x32_bf16 v[12:15], v[162:165], v[170:173], v[12:15]
	s_mov_b32 m0, s62
	v_lshl_add_u64 v[186:187], v[246:247], 0, s[94:95]
	global_load_lds_dwordx4 v[186:187], off
	v_mfma_f32_16x16x32_bf16 v[32:35], v[154:157], v[178:181], v[32:35]
	v_mfma_f32_16x16x32_bf16 v[8:11], v[162:165], v[178:181], v[8:11]
	v_mfma_f32_16x16x32_bf16 v[24:27], v[154:157], v[192:195], v[24:27]
	v_mfma_f32_16x16x32_bf16 v[4:7], v[162:165], v[192:195], v[4:7]
	v_mfma_f32_16x16x32_bf16 v[16:19], v[154:157], v[234:237], v[16:19]
	v_mfma_f32_16x16x32_bf16 v[0:3], v[162:165], v[234:237], v[0:3]
	v_mfma_f32_16x16x32_bf16 v[40:43], v[158:161], v[174:177], v[40:43]
	v_mfma_f32_16x16x32_bf16 v[12:15], v[166:169], v[174:177], v[12:15]
	s_mov_b32 m0, s63
	v_lshl_add_u64 v[186:187], v[248:249], 0, s[94:95]
	global_load_lds_dwordx4 v[186:187], off
	v_mfma_f32_16x16x32_bf16 v[32:35], v[158:161], v[182:185], v[32:35]
	v_mfma_f32_16x16x32_bf16 v[8:11], v[166:169], v[182:185], v[8:11]
	v_mfma_f32_16x16x32_bf16 v[24:27], v[158:161], v[230:233], v[24:27]
	v_mfma_f32_16x16x32_bf16 v[4:7], v[166:169], v[230:233], v[4:7]
	v_mfma_f32_16x16x32_bf16 v[16:19], v[158:161], v[238:241], v[16:19]
	v_mfma_f32_16x16x32_bf16 v[0:3], v[166:169], v[238:241], v[0:3]
	s_setprio 0
	s_barrier
	s_add_u32 s26, s26, 0x100
	s_addc_u32 s27, s27, 0
	s_add_u32 s72, s72, 0x100
	s_addc_u32 s73, s73, 0
	s_cmp_ge_u32 s74, s52
	s_mov_b32 s28, s74
	s_cbranch_scc0 .LBB0_1642
	s_and_b64 vcc, exec, s[14:15]
	s_cbranch_vccz .LBB0_1645
	s_barrier

; #define PG8_STAGE(bufoff, gbase, voff) do { _Pragma("unroll") for (int _i = 0; _i < 2; ++_i) \
;         __builtin_amdgcn_global_load_lds((const unsigned*)((const char*)(gbase) + (voff)[_i]), (PG8_LAS unsigned*)(lds + (bufoff) + ldsw + _i * 8192), 16, 0, 0); } while (0)
; #define PG8_LDA(dst, b, h) do { _Pragma("unroll") for (int m = 0; m < 4; ++m) _Pragma("unroll") for (int k = 0; k < 2; ++k) dst[m][k] = *(const PG8_LAS bf16x8*)(lds + PG8_SA(b, h) + aoff + m * 2048 + k * 1024); } while (0)
; #define PG8_LDB(dst, b, h) do { _Pragma("unroll") for (int n = 0; n < 2; ++n) _Pragma("unroll") for (int k = 0; k < 2; ++k) dst[n][k] = *(const PG8_LAS bf16x8*)(lds + PG8_SB(b, h) + boff + n * 2048 + k * 1024); } while (0)
; #define PG8_MMA(ai, bj, At, Bt) do { __builtin_amdgcn_s_setprio(1); _Pragma("unroll") for (int m = 0; m < 4; ++m) _Pragma("unroll") for (int n = 0; n < 2; ++n) _Pragma("unroll") for (int k = 0; k < 2; ++k) \
;         acc[ai][bj][m][n] = __builtin_amdgcn_mfma_f32_16x16x32_bf16(Bt[n][k], At[m][k], acc[ai][bj][m][n], 0, 0, 0); __builtin_amdgcn_s_setprio(0); } while (0)
; #define PG8_WAIT_V(n) asm volatile("s_waitcnt vmcnt(" #n ")" ::: "memory")
; #define PG8_WAIT_L(n) asm volatile("s_waitcnt lgkmcnt(" #n ")" ::: "memory")
; template <class Epi, class Sched, bool ALIGN_EPI = false, bool SP2 = false>
; __device__ __forceinline__ void gemm_phase(PG8_LAS unsigned char* lds, const Gemm g, const Sched& S, const Epi& E) {
;     ...
;             const bool last = (t == nt - 2);
;             const char* a1 = cA + (size_t)(t + 1) * kstep;
;             const char* a2 = last ? nA : cA + (size_t)(t + 2) * kstep; const char* b2 = last ? nB : cB + (size_t)(t + 2) * kstep;
;             const char* a3 = a2 + kstep; const char* b3 = b2 + kstep;
;             if (last && has_next) S.a_ready(nxt);
;             if constexpr (SP2) {
;             PG8_LDB(B0, 0, 0); PG8_LDB(B1, 0, 1); PG8_SCHED; PG8_LDA(At, 0, 0); PG8_STAGE(PG8_SA(1, 1), a1 + hstepA, voffA);
;             PG8_WAIT_V(8); PG8_WAIT_L(0); PG8_BAR; PG8_MMA(0, 0, At, B0); PG8_MMA(0, 1, At, B1); PG8_BAR; PG8_SCHED;
;             PG8_LDA(At, 0, 1); PG8_STAGE(PG8_SB(0, 0), b2, voffB); PG8_STAGE(PG8_SB(0, 1), b2 + hstepB, voffB); PG8_STAGE(PG8_SA(0, 0), a2, voffA);
;             PG8_WAIT_V(8); PG8_WAIT_L(0); PG8_BAR; PG8_MMA(1, 0, At, B0); PG8_MMA(1, 1, At, B1); PG8_BAR; PG8_SCHED;
.LBB0_1800:
	v_add_u32_e32 v140, 0x10000, v229
	v_add_u32_e32 v156, 0x14000, v229
	ds_read_b128 v[128:131], v140
	ds_read_b128 v[132:135], v140 offset:1024
	ds_read_b128 v[136:139], v140 offset:2048
	ds_read_b128 v[140:143], v140 offset:3072
	ds_read_b128 v[144:147], v156
	ds_read_b128 v[148:151], v156 offset:1024
	ds_read_b128 v[152:155], v156 offset:2048
	ds_read_b128 v[156:159], v156 offset:3072
	ds_read_b128 v[160:163], v230
	ds_read_b128 v[164:167], v230 offset:1024
	ds_read_b128 v[178:181], v230 offset:2048
	ds_read_b128 v[182:185], v230 offset:3072
	ds_read_b128 v[192:195], v230 offset:4096
	ds_read_b128 v[232:235], v230 offset:5120
	ds_read_b128 v[236:239], v230 offset:6144
	ds_read_b128 v[240:243], v230 offset:7168
	s_add_u32 s10, s8, 0xfffc0080
	s_addc_u32 s11, s9, -1
	s_add_i32 s71, 0, 0x10000
	s_cmp_eq_u32 s70, 12
	s_cselect_b32 s45, s13, s11
	s_cselect_b32 s44, s15, s10
	s_cselect_b32 s11, s35, s47
	s_cselect_b32 s10, s37, s46
	s_add_i32 s74, 0, 0x14000
	s_add_i32 m0, s54, 0xc000
	v_lshl_add_u64 v[186:187], s[8:9], 0, v[174:175]
	global_load_lds_dwordx4 v[186:187], off
	s_add_i32 m0, s54, 0xe000
	v_lshl_add_u64 v[186:187], s[8:9], 0, v[176:177]
	global_load_lds_dwordx4 v[186:187], off
	s_waitcnt vmcnt(8)
	s_waitcnt lgkmcnt(0)
	s_barrier
	s_setprio 1
	s_waitcnt lgkmcnt(0)
	v_mfma_f32_16x16x32_bf16 v[124:127], v[128:131], v[160:163], v[124:127]
	v_mfma_f32_16x16x32_bf16 v[60:63], v[136:139], v[160:163], v[60:63]
	v_mfma_f32_16x16x32_bf16 v[120:123], v[128:131], v[178:181], v[120:123]
	v_mfma_f32_16x16x32_bf16 v[56:59], v[136:139], v[178:181], v[56:59]
	v_mfma_f32_16x16x32_bf16 v[108:111], v[128:131], v[192:195], v[108:111]
	v_mfma_f32_16x16x32_bf16 v[44:47], v[136:139], v[192:195], v[44:47]
	v_mfma_f32_16x16x32_bf16 v[100:103], v[128:131], v[236:239], v[100:103]
	v_mfma_f32_16x16x32_bf16 v[36:39], v[136:139], v[236:239], v[36:39]
	v_mfma_f32_16x16x32_bf16 v[124:127], v[132:135], v[164:167], v[124:127]
	v_mfma_f32_16x16x32_bf16 v[60:63], v[140:143], v[164:167], v[60:63]
	v_mfma_f32_16x16x32_bf16 v[120:123], v[132:135], v[182:185], v[120:123]
	v_mfma_f32_16x16x32_bf16 v[56:59], v[140:143], v[182:185], v[56:59]
	v_mfma_f32_16x16x32_bf16 v[108:111], v[132:135], v[232:235], v[108:111]
	v_mfma_f32_16x16x32_bf16 v[44:47], v[140:143], v[232:235], v[44:47]
	v_mfma_f32_16x16x32_bf16 v[100:103], v[132:135], v[240:243], v[100:103]
	v_mfma_f32_16x16x32_bf16 v[36:39], v[140:143], v[240:243], v[36:39]
	s_setprio 0
	s_setprio 1
	v_mfma_f32_16x16x32_bf16 v[116:119], v[144:147], v[160:163], v[116:119]
	v_mfma_f32_16x16x32_bf16 v[52:55], v[152:155], v[160:163], v[52:55]
	v_mfma_f32_16x16x32_bf16 v[112:115], v[144:147], v[178:181], v[112:115]
	v_mfma_f32_16x16x32_bf16 v[48:51], v[152:155], v[178:181], v[48:51]
	v_mfma_f32_16x16x32_bf16 v[104:107], v[144:147], v[192:195], v[104:107]
	v_mfma_f32_16x16x32_bf16 v[40:43], v[152:155], v[192:195], v[40:43]
	v_mfma_f32_16x16x32_bf16 v[96:99], v[144:147], v[236:239], v[96:99]
	v_mfma_f32_16x16x32_bf16 v[32:35], v[152:155], v[236:239], v[32:35]
	v_mfma_f32_16x16x32_bf16 v[116:119], v[148:151], v[164:167], v[116:119]
	v_mfma_f32_16x16x32_bf16 v[52:55], v[156:159], v[164:167], v[52:55]
	v_mfma_f32_16x16x32_bf16 v[112:115], v[148:151], v[182:185], v[112:115]
	v_mfma_f32_16x16x32_bf16 v[48:51], v[156:159], v[182:185], v[48:51]
	v_mfma_f32_16x16x32_bf16 v[104:107], v[148:151], v[232:235], v[104:107]
	v_mfma_f32_16x16x32_bf16 v[40:43], v[156:159], v[232:235], v[40:43]
	v_mfma_f32_16x16x32_bf16 v[96:99], v[148:151], v[240:243], v[96:99]
	v_mfma_f32_16x16x32_bf16 v[32:35], v[156:159], v[240:243], v[32:35]
	s_setprio 0
	s_barrier
	ds_read_b128 v[160:163], v230 offset:16384
	ds_read_b128 v[164:167], v230 offset:17408
	ds_read_b128 v[178:181], v230 offset:18432
	ds_read_b128 v[182:185], v230 offset:19456
	ds_read_b128 v[192:195], v230 offset:20480
	ds_read_b128 v[232:235], v230 offset:21504
	ds_read_b128 v[236:239], v230 offset:22528
	ds_read_b128 v[240:243], v230 offset:23552
	s_add_i32 s71, s71, s53
	s_mov_b32 m0, s71
	v_lshl_add_u64 v[186:187], s[10:11], 0, v[188:189]
	global_load_lds_dwordx4 v[186:187], off
	s_add_i32 m0, s71, 0x2000
	s_add_u32 s72, s10, 0x40000
	v_lshl_add_u64 v[244:245], s[10:11], 0, v[172:173]
	s_addc_u32 s73, s11, 0
	s_add_i32 s71, s74, s53
	global_load_lds_dwordx4 v[244:245], off
	s_waitcnt vmcnt(4)
	s_waitcnt lgkmcnt(0)
	s_barrier
; #define PG8_STAGE(bufoff, gbase, voff) do { _Pragma("unroll") for (int _i = 0; _i < 2; ++_i) \
;         __builtin_amdgcn_global_load_lds((const unsigned*)((const char*)(gbase) + (voff)[_i]), (PG8_LAS unsigned*)(lds + (bufoff) + ldsw + _i * 8192), 16, 0, 0); } while (0)
; #define PG8_LDA(dst, b, h) do { _Pragma("unroll") for (int m = 0; m < 4; ++m) _Pragma("unroll") for (int k = 0; k < 2; ++k) dst[m][k] = *(const PG8_LAS bf16x8*)(lds + PG8_SA(b, h) + aoff + m * 2048 + k * 1024); } while (0)
; #define PG8_LDB(dst, b, h) do { _Pragma("unroll") for (int n = 0; n < 2; ++n) _Pragma("unroll") for (int k = 0; k < 2; ++k) dst[n][k] = *(const PG8_LAS bf16x8*)(lds + PG8_SB(b, h) + boff + n * 2048 + k * 1024); } while (0)
; #define PG8_MMA(ai, bj, At, Bt) do { __builtin_amdgcn_s_setprio(1); _Pragma("unroll") for (int m = 0; m < 4; ++m) _Pragma("unroll") for (int n = 0; n < 2; ++n) _Pragma("unroll") for (int k = 0; k < 2; ++k) \
;         acc[ai][bj][m][n] = __builtin_amdgcn_mfma_f32_16x16x32_bf16(Bt[n][k], At[m][k], acc[ai][bj][m][n], 0, 0, 0); __builtin_amdgcn_s_setprio(0); } while (0)
; #define PG8_WAIT_V(n) asm volatile("s_waitcnt vmcnt(" #n ")" ::: "memory")
; #define PG8_WAIT_L(n) asm volatile("s_waitcnt lgkmcnt(" #n ")" ::: "memory")
; #define PG8_BAR __builtin_amdgcn_s_barrier()
; #define PG8_SCHED __builtin_amdgcn_sched_barrier(0)
; template <class Epi, class Sched, bool ALIGN_EPI = false, bool SP2 = false>
; __device__ __forceinline__ void gemm_phase(PG8_LAS unsigned char* lds, const Gemm g, const Sched& S, const Epi& E) {
;     ...
;             PG8_WAIT_V(8); PG8_WAIT_L(0); PG8_BAR; PG8_MMA(1, 0, At, B0); PG8_MMA(1, 1, At, B1); PG8_BAR; PG8_SCHED;
;             PG8_LDB(B0, 1, 0); PG8_LDB(B1, 1, 1); PG8_SCHED; PG8_LDA(At, 1, 0); PG8_STAGE(PG8_SA(0, 1), a2 + hstepA, voffA);
;             PG8_WAIT_V(8); PG8_WAIT_L(0); PG8_BAR; PG8_MMA(0, 0, At, B0); PG8_MMA(0, 1, At, B1); PG8_BAR; PG8_SCHED;
	s_setprio 1
	s_waitcnt lgkmcnt(0)
	v_mfma_f32_16x16x32_bf16 v[92:95], v[128:131], v[160:163], v[92:95]
	v_mfma_f32_16x16x32_bf16 v[28:31], v[136:139], v[160:163], v[28:31]
	v_lshl_add_u64 v[246:247], s[72:73], 0, v[188:189]
	s_mov_b32 m0, s71
	v_lshl_add_u64 v[248:249], s[44:45], 0, v[170:171]
	global_load_lds_dwordx4 v[246:247], off
	v_mfma_f32_16x16x32_bf16 v[88:91], v[128:131], v[178:181], v[88:91]
	v_mfma_f32_16x16x32_bf16 v[24:27], v[136:139], v[178:181], v[24:27]
	v_mfma_f32_16x16x32_bf16 v[76:79], v[128:131], v[192:195], v[76:79]
	v_mfma_f32_16x16x32_bf16 v[12:15], v[136:139], v[192:195], v[12:15]
	v_mfma_f32_16x16x32_bf16 v[68:71], v[128:131], v[236:239], v[68:71]
	v_mfma_f32_16x16x32_bf16 v[4:7], v[136:139], v[236:239], v[4:7]
	v_mfma_f32_16x16x32_bf16 v[92:95], v[132:135], v[164:167], v[92:95]
	v_mfma_f32_16x16x32_bf16 v[28:31], v[140:143], v[164:167], v[28:31]
	s_add_i32 m0, s71, 0x2000
	v_lshl_add_u64 v[246:247], s[72:73], 0, v[172:173]
	global_load_lds_dwordx4 v[246:247], off
	v_mfma_f32_16x16x32_bf16 v[88:91], v[132:135], v[182:185], v[88:91]
	v_mfma_f32_16x16x32_bf16 v[24:27], v[140:143], v[182:185], v[24:27]
	v_mfma_f32_16x16x32_bf16 v[76:79], v[132:135], v[232:235], v[76:79]
	v_mfma_f32_16x16x32_bf16 v[12:15], v[140:143], v[232:235], v[12:15]
	v_mfma_f32_16x16x32_bf16 v[68:71], v[132:135], v[240:243], v[68:71]
	v_mfma_f32_16x16x32_bf16 v[4:7], v[140:143], v[240:243], v[4:7]
	s_setprio 0
	s_setprio 1
	v_mfma_f32_16x16x32_bf16 v[84:87], v[144:147], v[160:163], v[84:87]
	v_mfma_f32_16x16x32_bf16 v[20:23], v[152:155], v[160:163], v[20:23]
	s_mov_b32 m0, s54
	v_lshl_add_u64 v[246:247], s[44:45], 0, v[168:169]
	global_load_lds_dwordx4 v[246:247], off
	v_mfma_f32_16x16x32_bf16 v[80:83], v[144:147], v[178:181], v[80:83]
	v_mfma_f32_16x16x32_bf16 v[16:19], v[152:155], v[178:181], v[16:19]
	v_mfma_f32_16x16x32_bf16 v[72:75], v[144:147], v[192:195], v[72:75]
	v_mfma_f32_16x16x32_bf16 v[8:11], v[152:155], v[192:195], v[8:11]
	v_mfma_f32_16x16x32_bf16 v[64:67], v[144:147], v[236:239], v[64:67]
	v_mfma_f32_16x16x32_bf16 v[0:3], v[152:155], v[236:239], v[0:3]
	v_mfma_f32_16x16x32_bf16 v[84:87], v[148:151], v[164:167], v[84:87]
	v_mfma_f32_16x16x32_bf16 v[20:23], v[156:159], v[164:167], v[20:23]
	s_mov_b32 m0, s55
	s_nop 0
	global_load_lds_dwordx4 v[248:249], off
	v_mfma_f32_16x16x32_bf16 v[80:83], v[148:151], v[182:185], v[80:83]
	v_mfma_f32_16x16x32_bf16 v[16:19], v[156:159], v[182:185], v[16:19]
	v_mfma_f32_16x16x32_bf16 v[72:75], v[148:151], v[232:235], v[72:75]
	v_mfma_f32_16x16x32_bf16 v[8:11], v[156:159], v[232:235], v[8:11]
	v_mfma_f32_16x16x32_bf16 v[64:67], v[148:151], v[240:243], v[64:67]
	v_mfma_f32_16x16x32_bf16 v[0:3], v[156:159], v[240:243], v[0:3]
	s_setprio 0
	s_barrier
	v_add_u32_e32 v140, 0x18000, v229
	v_add_u32_e32 v156, 0x1c000, v229
	ds_read_b128 v[128:131], v140
	ds_read_b128 v[132:135], v140 offset:1024
	ds_read_b128 v[136:139], v140 offset:2048
	ds_read_b128 v[140:143], v140 offset:3072
	ds_read_b128 v[144:147], v156
	ds_read_b128 v[148:151], v156 offset:1024
	ds_read_b128 v[152:155], v156 offset:2048
	ds_read_b128 v[156:159], v156 offset:3072
	ds_read_b128 v[160:163], v230 offset:32768
	ds_read_b128 v[164:167], v230 offset:33792
	ds_read_b128 v[178:181], v230 offset:34816
	ds_read_b128 v[182:185], v230 offset:35840
	ds_read_b128 v[192:195], v230 offset:36864
	ds_read_b128 v[232:235], v230 offset:37888
	ds_read_b128 v[236:239], v230 offset:38912
	ds_read_b128 v[240:243], v230 offset:39936
	s_add_i32 s71, 0, 0x18000
	s_add_i32 s72, 0, 0x1c000
	s_add_u32 s44, s44, 0x40000
	s_addc_u32 s45, s45, 0
	s_mov_b32 m0, s56
	v_lshl_add_u64 v[250:251], s[44:45], 0, v[168:169]
	global_load_lds_dwordx4 v[250:251], off
	s_mov_b32 m0, s57
	v_lshl_add_u64 v[250:251], s[44:45], 0, v[170:171]
	global_load_lds_dwordx4 v[250:251], off
	s_waitcnt vmcnt(8)
	s_waitcnt lgkmcnt(0)
	s_barrier
; #define PG8_STAGE(bufoff, gbase, voff) do { _Pragma("unroll") for (int _i = 0; _i < 2; ++_i) \
;         __builtin_amdgcn_global_load_lds((const unsigned*)((const char*)(gbase) + (voff)[_i]), (PG8_LAS unsigned*)(lds + (bufoff) + ldsw + _i * 8192), 16, 0, 0); } while (0)
; #define PG8_LDA(dst, b, h) do { _Pragma("unroll") for (int m = 0; m < 4; ++m) _Pragma("unroll") for (int k = 0; k < 2; ++k) dst[m][k] = *(const PG8_LAS bf16x8*)(lds + PG8_SA(b, h) + aoff + m * 2048 + k * 1024); } while (0)
; #define PG8_MMA(ai, bj, At, Bt) do { __builtin_amdgcn_s_setprio(1); _Pragma("unroll") for (int m = 0; m < 4; ++m) _Pragma("unroll") for (int n = 0; n < 2; ++n) _Pragma("unroll") for (int k = 0; k < 2; ++k) \
;         acc[ai][bj][m][n] = __builtin_amdgcn_mfma_f32_16x16x32_bf16(Bt[n][k], At[m][k], acc[ai][bj][m][n], 0, 0, 0); __builtin_amdgcn_s_setprio(0); } while (0)
; #define PG8_WAIT_V(n) asm volatile("s_waitcnt vmcnt(" #n ")" ::: "memory")
; #define PG8_WAIT_L(n) asm volatile("s_waitcnt lgkmcnt(" #n ")" ::: "memory")
; #define PG8_BAR __builtin_amdgcn_s_barrier()
; #define PG8_SCHED __builtin_amdgcn_sched_barrier(0)
; template <class Epi, class Sched, bool ALIGN_EPI = false, bool SP2 = false>
; __device__ __forceinline__ void gemm_phase(PG8_LAS unsigned char* lds, const Gemm g, const Sched& S, const Epi& E) {
;     ...
;         for (int t = 0; t < nt; t += 2) {
;     ...
;             PG8_WAIT_V(8); PG8_WAIT_L(0); PG8_BAR; PG8_MMA(0, 0, At, B0); PG8_MMA(0, 1, At, B1); PG8_BAR; PG8_SCHED;
;             PG8_LDA(At, 1, 1); PG8_STAGE(PG8_SB(1, 0), b3, voffB); PG8_STAGE(PG8_SB(1, 1), b3 + hstepB, voffB); PG8_STAGE(PG8_SA(1, 0), a3, voffA);
;             PG8_WAIT_V(8); PG8_WAIT_L(0); PG8_BAR; PG8_MMA(1, 0, At, B0); PG8_MMA(1, 1, At, B1); PG8_BAR; PG8_SCHED;
	s_setprio 1
	s_waitcnt lgkmcnt(0)
	v_mfma_f32_16x16x32_bf16 v[124:127], v[128:131], v[160:163], v[124:127]
	v_mfma_f32_16x16x32_bf16 v[60:63], v[136:139], v[160:163], v[60:63]
	v_mfma_f32_16x16x32_bf16 v[120:123], v[128:131], v[178:181], v[120:123]
	v_mfma_f32_16x16x32_bf16 v[56:59], v[136:139], v[178:181], v[56:59]
	v_mfma_f32_16x16x32_bf16 v[108:111], v[128:131], v[192:195], v[108:111]
	v_mfma_f32_16x16x32_bf16 v[44:47], v[136:139], v[192:195], v[44:47]
	v_mfma_f32_16x16x32_bf16 v[100:103], v[128:131], v[236:239], v[100:103]
	v_mfma_f32_16x16x32_bf16 v[36:39], v[136:139], v[236:239], v[36:39]
	v_mfma_f32_16x16x32_bf16 v[124:127], v[132:135], v[164:167], v[124:127]
	v_mfma_f32_16x16x32_bf16 v[60:63], v[140:143], v[164:167], v[60:63]
	v_mfma_f32_16x16x32_bf16 v[120:123], v[132:135], v[182:185], v[120:123]
	v_mfma_f32_16x16x32_bf16 v[56:59], v[140:143], v[182:185], v[56:59]
	v_mfma_f32_16x16x32_bf16 v[108:111], v[132:135], v[232:235], v[108:111]
	v_mfma_f32_16x16x32_bf16 v[44:47], v[140:143], v[232:235], v[44:47]
	v_mfma_f32_16x16x32_bf16 v[100:103], v[132:135], v[240:243], v[100:103]
	v_mfma_f32_16x16x32_bf16 v[36:39], v[140:143], v[240:243], v[36:39]
	s_setprio 0
	s_setprio 1
	v_mfma_f32_16x16x32_bf16 v[116:119], v[144:147], v[160:163], v[116:119]
	v_mfma_f32_16x16x32_bf16 v[52:55], v[152:155], v[160:163], v[52:55]
	v_mfma_f32_16x16x32_bf16 v[112:115], v[144:147], v[178:181], v[112:115]
	v_mfma_f32_16x16x32_bf16 v[48:51], v[152:155], v[178:181], v[48:51]
	v_mfma_f32_16x16x32_bf16 v[104:107], v[144:147], v[192:195], v[104:107]
	v_mfma_f32_16x16x32_bf16 v[40:43], v[152:155], v[192:195], v[40:43]
	v_mfma_f32_16x16x32_bf16 v[96:99], v[144:147], v[236:239], v[96:99]
	v_mfma_f32_16x16x32_bf16 v[32:35], v[152:155], v[236:239], v[32:35]
	v_mfma_f32_16x16x32_bf16 v[116:119], v[148:151], v[164:167], v[116:119]
	v_mfma_f32_16x16x32_bf16 v[52:55], v[156:159], v[164:167], v[52:55]
	v_mfma_f32_16x16x32_bf16 v[112:115], v[148:151], v[182:185], v[112:115]
	v_mfma_f32_16x16x32_bf16 v[48:51], v[156:159], v[182:185], v[48:51]
	v_mfma_f32_16x16x32_bf16 v[104:107], v[148:151], v[232:235], v[104:107]
	v_mfma_f32_16x16x32_bf16 v[40:43], v[156:159], v[232:235], v[40:43]
	v_mfma_f32_16x16x32_bf16 v[96:99], v[148:151], v[240:243], v[96:99]
	v_mfma_f32_16x16x32_bf16 v[32:35], v[156:159], v[240:243], v[32:35]
	s_setprio 0
	s_barrier
	ds_read_b128 v[160:163], v230 offset:49152
	ds_read_b128 v[164:167], v230 offset:50176
	ds_read_b128 v[178:181], v230 offset:51200
	ds_read_b128 v[182:185], v230 offset:52224
	ds_read_b128 v[192:195], v230 offset:53248
	ds_read_b128 v[232:235], v230 offset:54272
	ds_read_b128 v[236:239], v230 offset:55296
	ds_read_b128 v[240:243], v230 offset:56320
	s_add_i32 s44, s71, s53
	s_mov_b32 m0, s44
	v_lshl_add_u64 v[186:187], v[186:187], 0, s[94:95]
	global_load_lds_dwordx4 v[186:187], off
	s_add_i32 m0, s44, 0x2000
	s_add_u32 s10, s10, 0x40080
	v_lshl_add_u64 v[186:187], v[244:245], 0, s[94:95]
	s_addc_u32 s11, s11, 0
	s_add_i32 s44, s72, s53
	global_load_lds_dwordx4 v[186:187], off
	s_waitcnt vmcnt(4)
	s_waitcnt lgkmcnt(0)
	s_barrier
	s_setprio 1
	s_waitcnt lgkmcnt(0)
	v_mfma_f32_16x16x32_bf16 v[92:95], v[128:131], v[160:163], v[92:95]
	v_mfma_f32_16x16x32_bf16 v[28:31], v[136:139], v[160:163], v[28:31]
	s_mov_b32 m0, s44
	v_lshl_add_u64 v[186:187], s[10:11], 0, v[188:189]
	global_load_lds_dwordx4 v[186:187], off
	v_mfma_f32_16x16x32_bf16 v[88:91], v[128:131], v[178:181], v[88:91]
	v_mfma_f32_16x16x32_bf16 v[24:27], v[136:139], v[178:181], v[24:27]
	v_mfma_f32_16x16x32_bf16 v[76:79], v[128:131], v[192:195], v[76:79]
	v_mfma_f32_16x16x32_bf16 v[12:15], v[136:139], v[192:195], v[12:15]
	v_mfma_f32_16x16x32_bf16 v[68:71], v[128:131], v[236:239], v[68:71]
	v_mfma_f32_16x16x32_bf16 v[4:7], v[136:139], v[236:239], v[4:7]
	v_mfma_f32_16x16x32_bf16 v[92:95], v[132:135], v[164:167], v[92:95]
	v_mfma_f32_16x16x32_bf16 v[28:31], v[140:143], v[164:167], v[28:31]
	s_add_i32 m0, s44, 0x2000
	v_lshl_add_u64 v[186:187], s[10:11], 0, v[172:173]
	global_load_lds_dwordx4 v[186:187], off
	v_mfma_f32_16x16x32_bf16 v[88:91], v[132:135], v[182:185], v[88:91]
	v_mfma_f32_16x16x32_bf16 v[24:27], v[140:143], v[182:185], v[24:27]
	v_mfma_f32_16x16x32_bf16 v[76:79], v[132:135], v[232:235], v[76:79]
	v_mfma_f32_16x16x32_bf16 v[12:15], v[140:143], v[232:235], v[12:15]
	v_mfma_f32_16x16x32_bf16 v[68:71], v[132:135], v[240:243], v[68:71]
	v_mfma_f32_16x16x32_bf16 v[4:7], v[140:143], v[240:243], v[4:7]
	s_setprio 0
	s_setprio 1
	v_mfma_f32_16x16x32_bf16 v[84:87], v[144:147], v[160:163], v[84:87]
	v_mfma_f32_16x16x32_bf16 v[20:23], v[152:155], v[160:163], v[20:23]
	s_mov_b32 m0, s60
	v_lshl_add_u64 v[186:187], v[246:247], 0, s[94:95]
	global_load_lds_dwordx4 v[186:187], off
	v_mfma_f32_16x16x32_bf16 v[80:83], v[144:147], v[178:181], v[80:83]
	v_mfma_f32_16x16x32_bf16 v[16:19], v[152:155], v[178:181], v[16:19]
	v_mfma_f32_16x16x32_bf16 v[72:75], v[144:147], v[192:195], v[72:75]
	v_mfma_f32_16x16x32_bf16 v[8:11], v[152:155], v[192:195], v[8:11]
	v_mfma_f32_16x16x32_bf16 v[64:67], v[144:147], v[236:239], v[64:67]
	v_mfma_f32_16x16x32_bf16 v[0:3], v[152:155], v[236:239], v[0:3]
	v_mfma_f32_16x16x32_bf16 v[84:87], v[148:151], v[164:167], v[84:87]
	v_mfma_f32_16x16x32_bf16 v[20:23], v[156:159], v[164:167], v[20:23]
	s_mov_b32 m0, s61
	v_lshl_add_u64 v[186:187], v[248:249], 0, s[94:95]
	global_load_lds_dwordx4 v[186:187], off
	v_mfma_f32_16x16x32_bf16 v[80:83], v[148:151], v[182:185], v[80:83]
	v_mfma_f32_16x16x32_bf16 v[16:19], v[156:159], v[182:185], v[16:19]
	v_mfma_f32_16x16x32_bf16 v[72:75], v[148:151], v[232:235], v[72:75]
	v_mfma_f32_16x16x32_bf16 v[8:11], v[156:159], v[232:235], v[8:11]
	v_mfma_f32_16x16x32_bf16 v[64:67], v[148:151], v[240:243], v[64:67]
	v_mfma_f32_16x16x32_bf16 v[0:3], v[156:159], v[240:243], v[0:3]
	s_setprio 0
	s_barrier
	s_add_i32 s70, s70, 2
	s_add_u32 s8, s8, 0x100
	s_addc_u32 s9, s9, 0
	s_add_u32 s46, s46, 0x100
	s_addc_u32 s47, s47, 0
	s_cmp_gt_u32 s70, 13
	s_cbranch_scc0 .LBB0_1800
	s_and_b64 vcc, exec, s[26:27]
	s_cbranch_vccz .LBB0_1803
	s_barrier

; #define PG8_STAGE(bufoff, gbase, voff) do { _Pragma("unroll") for (int _i = 0; _i < 2; ++_i) \
;         __builtin_amdgcn_global_load_lds((const unsigned*)((const char*)(gbase) + (voff)[_i]), (PG8_LAS unsigned*)(lds + (bufoff) + ldsw + _i * 8192), 16, 0, 0); } while (0)
; #define PG8_LDA(dst, b, h) do { _Pragma("unroll") for (int m = 0; m < 4; ++m) _Pragma("unroll") for (int k = 0; k < 2; ++k) dst[m][k] = *(const PG8_LAS bf16x8*)(lds + PG8_SA(b, h) + aoff + m * 2048 + k * 1024); } while (0)
; #define PG8_LDB(dst, b, h) do { _Pragma("unroll") for (int n = 0; n < 2; ++n) _Pragma("unroll") for (int k = 0; k < 2; ++k) dst[n][k] = *(const PG8_LAS bf16x8*)(lds + PG8_SB(b, h) + boff + n * 2048 + k * 1024); } while (0)
; #define PG8_MMA(ai, bj, At, Bt) do { __builtin_amdgcn_s_setprio(1); _Pragma("unroll") for (int m = 0; m < 4; ++m) _Pragma("unroll") for (int n = 0; n < 2; ++n) _Pragma("unroll") for (int k = 0; k < 2; ++k) \
;         acc[ai][bj][m][n] = __builtin_amdgcn_mfma_f32_16x16x32_bf16(Bt[n][k], At[m][k], acc[ai][bj][m][n], 0, 0, 0); __builtin_amdgcn_s_setprio(0); } while (0)
; #define PG8_WAIT_V(n) asm volatile("s_waitcnt vmcnt(" #n ")" ::: "memory")
; #define PG8_WAIT_L(n) asm volatile("s_waitcnt lgkmcnt(" #n ")" ::: "memory")
; template <class Epi, class Sched, bool ALIGN_EPI = false, bool SP2 = false>
; __device__ __forceinline__ void gemm_phase(PG8_LAS unsigned char* lds, const Gemm g, const Sched& S, const Epi& E) {
;     ...
;             const bool last = (t == nt - 2);
;             const char* a1 = cA + (size_t)(t + 1) * kstep;
;             const char* a2 = last ? nA : cA + (size_t)(t + 2) * kstep; const char* b2 = last ? nB : cB + (size_t)(t + 2) * kstep;
;             const char* a3 = a2 + kstep; const char* b3 = b2 + kstep;
;             if (last && has_next) S.a_ready(nxt);
;             if constexpr (SP2) {
;             PG8_LDB(B0, 0, 0); PG8_LDB(B1, 0, 1); PG8_SCHED; PG8_LDA(At, 0, 0); PG8_STAGE(PG8_SA(1, 1), a1 + hstepA, voffA);
;             PG8_WAIT_V(8); PG8_WAIT_L(0); PG8_BAR; PG8_MMA(0, 0, At, B0); PG8_MMA(0, 1, At, B1); PG8_BAR; PG8_SCHED;
;             PG8_LDA(At, 0, 1); PG8_STAGE(PG8_SB(0, 0), b2, voffB); PG8_STAGE(PG8_SB(0, 1), b2 + hstepB, voffB); PG8_STAGE(PG8_SA(0, 0), a2, voffA);
;             PG8_WAIT_V(8); PG8_WAIT_L(0); PG8_BAR; PG8_MMA(1, 0, At, B0); PG8_MMA(1, 1, At, B1); PG8_BAR; PG8_SCHED;
.LBB0_1993:
	v_add_u32_e32 v150, 0x10000, v140
	v_add_u32_e32 v166, 0x14000, v140
	ds_read_b128 v[134:137], v150
	ds_read_b128 v[142:145], v150 offset:1024
	ds_read_b128 v[146:149], v150 offset:2048
	ds_read_b128 v[150:153], v150 offset:3072
	ds_read_b128 v[154:157], v166
	ds_read_b128 v[158:161], v166 offset:1024
	ds_read_b128 v[162:165], v166 offset:2048
	ds_read_b128 v[166:169], v166 offset:3072
	ds_read_b128 v[170:173], v141
	ds_read_b128 v[174:177], v141 offset:1024
	ds_read_b128 v[178:181], v141 offset:2048
	ds_read_b128 v[182:185], v141 offset:3072
	ds_read_b128 v[192:195], v141 offset:4096
	ds_read_b128 v[230:233], v141 offset:5120
	ds_read_b128 v[234:237], v141 offset:6144
	ds_read_b128 v[238:241], v141 offset:7168
	s_add_u32 s24, s22, 0x100
	s_addc_u32 s25, s23, 0
	s_add_i32 s68, 0, 0x10000
	s_cmp_eq_u32 s67, 40
	s_cselect_b32 s29, s9, s25
	s_cselect_b32 s28, s8, s24
	s_cselect_b32 s27, s21, s66
	s_cselect_b32 s26, s20, s65
	s_add_i32 s69, 0, 0x14000
	s_add_i32 m0, s36, 0xc000
	v_lshl_add_u64 v[186:187], s[22:23], 0, v[130:131]
	global_load_lds_dwordx4 v[186:187], off
	s_add_i32 m0, s36, 0xe000
	v_lshl_add_u64 v[186:187], s[22:23], 0, v[132:133]
	global_load_lds_dwordx4 v[186:187], off
	s_waitcnt vmcnt(8)
	s_waitcnt lgkmcnt(0)
	s_barrier
	s_setprio 1
	s_waitcnt lgkmcnt(0)
	v_mfma_f32_16x16x32_bf16 v[124:127], v[134:137], v[170:173], v[124:127]
	v_mfma_f32_16x16x32_bf16 v[96:99], v[146:149], v[170:173], v[96:99]
	v_mfma_f32_16x16x32_bf16 v[120:123], v[134:137], v[178:181], v[120:123]
	v_mfma_f32_16x16x32_bf16 v[92:95], v[146:149], v[178:181], v[92:95]
	v_mfma_f32_16x16x32_bf16 v[116:119], v[134:137], v[192:195], v[116:119]
	v_mfma_f32_16x16x32_bf16 v[84:87], v[146:149], v[192:195], v[84:87]
	v_mfma_f32_16x16x32_bf16 v[112:115], v[134:137], v[234:237], v[112:115]
	v_mfma_f32_16x16x32_bf16 v[80:83], v[146:149], v[234:237], v[80:83]
	v_mfma_f32_16x16x32_bf16 v[124:127], v[142:145], v[174:177], v[124:127]
	v_mfma_f32_16x16x32_bf16 v[96:99], v[150:153], v[174:177], v[96:99]
	v_mfma_f32_16x16x32_bf16 v[120:123], v[142:145], v[182:185], v[120:123]
	v_mfma_f32_16x16x32_bf16 v[92:95], v[150:153], v[182:185], v[92:95]
	v_mfma_f32_16x16x32_bf16 v[116:119], v[142:145], v[230:233], v[116:119]
	v_mfma_f32_16x16x32_bf16 v[84:87], v[150:153], v[230:233], v[84:87]
	v_mfma_f32_16x16x32_bf16 v[112:115], v[142:145], v[238:241], v[112:115]
	v_mfma_f32_16x16x32_bf16 v[80:83], v[150:153], v[238:241], v[80:83]
	s_setprio 0
	s_setprio 1
	v_mfma_f32_16x16x32_bf16 v[64:67], v[154:157], v[170:173], v[64:67]
	v_mfma_f32_16x16x32_bf16 v[36:39], v[162:165], v[170:173], v[36:39]
	v_mfma_f32_16x16x32_bf16 v[56:59], v[154:157], v[178:181], v[56:59]
	v_mfma_f32_16x16x32_bf16 v[24:27], v[162:165], v[178:181], v[24:27]
	v_mfma_f32_16x16x32_bf16 v[52:55], v[154:157], v[192:195], v[52:55]
	v_mfma_f32_16x16x32_bf16 v[20:23], v[162:165], v[192:195], v[20:23]
	v_mfma_f32_16x16x32_bf16 v[48:51], v[154:157], v[234:237], v[48:51]
	v_mfma_f32_16x16x32_bf16 v[16:19], v[162:165], v[234:237], v[16:19]
	v_mfma_f32_16x16x32_bf16 v[64:67], v[158:161], v[174:177], v[64:67]
	v_mfma_f32_16x16x32_bf16 v[36:39], v[166:169], v[174:177], v[36:39]
	v_mfma_f32_16x16x32_bf16 v[56:59], v[158:161], v[182:185], v[56:59]
	v_mfma_f32_16x16x32_bf16 v[24:27], v[166:169], v[182:185], v[24:27]
	v_mfma_f32_16x16x32_bf16 v[52:55], v[158:161], v[230:233], v[52:55]
	v_mfma_f32_16x16x32_bf16 v[20:23], v[166:169], v[230:233], v[20:23]
	v_mfma_f32_16x16x32_bf16 v[48:51], v[158:161], v[238:241], v[48:51]
	v_mfma_f32_16x16x32_bf16 v[16:19], v[166:169], v[238:241], v[16:19]
	s_setprio 0
	s_barrier
	ds_read_b128 v[170:173], v141 offset:16384
	ds_read_b128 v[174:177], v141 offset:17408
	ds_read_b128 v[178:181], v141 offset:18432
	ds_read_b128 v[182:185], v141 offset:19456
	ds_read_b128 v[192:195], v141 offset:20480
	ds_read_b128 v[230:233], v141 offset:21504
	ds_read_b128 v[234:237], v141 offset:22528
	ds_read_b128 v[238:241], v141 offset:23552
	s_add_i32 s22, s68, s35
	s_mov_b32 m0, s22
	v_lshl_add_u64 v[186:187], s[26:27], 0, v[188:189]
	global_load_lds_dwordx4 v[186:187], off
	s_add_i32 m0, s22, 0x2000
	s_add_u32 s22, s26, 0xb0000
	v_lshl_add_u64 v[196:197], s[26:27], 0, v[128:129]
	s_addc_u32 s23, s27, 0
	s_add_i32 s68, s69, s35
	global_load_lds_dwordx4 v[196:197], off
	s_waitcnt vmcnt(4)
	s_waitcnt lgkmcnt(0)
	s_barrier
; #define PG8_STAGE(bufoff, gbase, voff) do { _Pragma("unroll") for (int _i = 0; _i < 2; ++_i) \
;         __builtin_amdgcn_global_load_lds((const unsigned*)((const char*)(gbase) + (voff)[_i]), (PG8_LAS unsigned*)(lds + (bufoff) + ldsw + _i * 8192), 16, 0, 0); } while (0)
; #define PG8_LDA(dst, b, h) do { _Pragma("unroll") for (int m = 0; m < 4; ++m) _Pragma("unroll") for (int k = 0; k < 2; ++k) dst[m][k] = *(const PG8_LAS bf16x8*)(lds + PG8_SA(b, h) + aoff + m * 2048 + k * 1024); } while (0)
; #define PG8_LDB(dst, b, h) do { _Pragma("unroll") for (int n = 0; n < 2; ++n) _Pragma("unroll") for (int k = 0; k < 2; ++k) dst[n][k] = *(const PG8_LAS bf16x8*)(lds + PG8_SB(b, h) + boff + n * 2048 + k * 1024); } while (0)
; #define PG8_MMA(ai, bj, At, Bt) do { __builtin_amdgcn_s_setprio(1); _Pragma("unroll") for (int m = 0; m < 4; ++m) _Pragma("unroll") for (int n = 0; n < 2; ++n) _Pragma("unroll") for (int k = 0; k < 2; ++k) \
;         acc[ai][bj][m][n] = __builtin_amdgcn_mfma_f32_16x16x32_bf16(Bt[n][k], At[m][k], acc[ai][bj][m][n], 0, 0, 0); __builtin_amdgcn_s_setprio(0); } while (0)
; #define PG8_WAIT_V(n) asm volatile("s_waitcnt vmcnt(" #n ")" ::: "memory")
; #define PG8_WAIT_L(n) asm volatile("s_waitcnt lgkmcnt(" #n ")" ::: "memory")
; #define PG8_BAR __builtin_amdgcn_s_barrier()
; #define PG8_SCHED __builtin_amdgcn_sched_barrier(0)
; template <class Epi, class Sched, bool ALIGN_EPI = false, bool SP2 = false>
; __device__ __forceinline__ void gemm_phase(PG8_LAS unsigned char* lds, const Gemm g, const Sched& S, const Epi& E) {
;     ...
;             PG8_WAIT_V(8); PG8_WAIT_L(0); PG8_BAR; PG8_MMA(1, 0, At, B0); PG8_MMA(1, 1, At, B1); PG8_BAR; PG8_SCHED;
;             PG8_LDB(B0, 1, 0); PG8_LDB(B1, 1, 1); PG8_SCHED; PG8_LDA(At, 1, 0); PG8_STAGE(PG8_SA(0, 1), a2 + hstepA, voffA);
;             PG8_WAIT_V(8); PG8_WAIT_L(0); PG8_BAR; PG8_MMA(0, 0, At, B0); PG8_MMA(0, 1, At, B1); PG8_BAR; PG8_SCHED;
	s_setprio 1
	s_waitcnt lgkmcnt(0)
	v_mfma_f32_16x16x32_bf16 v[108:111], v[134:137], v[170:173], v[108:111]
	v_mfma_f32_16x16x32_bf16 v[76:79], v[146:149], v[170:173], v[76:79]
	v_lshl_add_u64 v[242:243], s[22:23], 0, v[188:189]
	s_mov_b32 m0, s68
	v_lshl_add_u64 v[244:245], s[28:29], 0, v[128:129]
	global_load_lds_dwordx4 v[242:243], off
	v_mfma_f32_16x16x32_bf16 v[104:107], v[134:137], v[178:181], v[104:107]
	v_mfma_f32_16x16x32_bf16 v[72:75], v[146:149], v[178:181], v[72:75]
	v_mfma_f32_16x16x32_bf16 v[100:103], v[134:137], v[192:195], v[100:103]
	v_mfma_f32_16x16x32_bf16 v[68:71], v[146:149], v[192:195], v[68:71]
	v_mfma_f32_16x16x32_bf16 v[88:91], v[134:137], v[234:237], v[88:91]
	v_mfma_f32_16x16x32_bf16 v[60:63], v[146:149], v[234:237], v[60:63]
	v_mfma_f32_16x16x32_bf16 v[108:111], v[142:145], v[174:177], v[108:111]
	v_mfma_f32_16x16x32_bf16 v[76:79], v[150:153], v[174:177], v[76:79]
	s_add_i32 m0, s68, 0x2000
	v_lshl_add_u64 v[242:243], s[22:23], 0, v[128:129]
	global_load_lds_dwordx4 v[242:243], off
	v_mfma_f32_16x16x32_bf16 v[104:107], v[142:145], v[182:185], v[104:107]
	v_mfma_f32_16x16x32_bf16 v[72:75], v[150:153], v[182:185], v[72:75]
	v_mfma_f32_16x16x32_bf16 v[100:103], v[142:145], v[230:233], v[100:103]
	v_mfma_f32_16x16x32_bf16 v[68:71], v[150:153], v[230:233], v[68:71]
	v_mfma_f32_16x16x32_bf16 v[88:91], v[142:145], v[238:241], v[88:91]
	v_mfma_f32_16x16x32_bf16 v[60:63], v[150:153], v[238:241], v[60:63]
	s_setprio 0
	s_setprio 1
	v_mfma_f32_16x16x32_bf16 v[44:47], v[154:157], v[170:173], v[44:47]
	v_mfma_f32_16x16x32_bf16 v[12:15], v[162:165], v[170:173], v[12:15]
	s_mov_b32 m0, s36
	v_lshl_add_u64 v[242:243], s[28:29], 0, v[188:189]
	global_load_lds_dwordx4 v[242:243], off
	v_mfma_f32_16x16x32_bf16 v[40:43], v[154:157], v[178:181], v[40:43]
	v_mfma_f32_16x16x32_bf16 v[8:11], v[162:165], v[178:181], v[8:11]
	v_mfma_f32_16x16x32_bf16 v[32:35], v[154:157], v[192:195], v[32:35]
	v_mfma_f32_16x16x32_bf16 v[4:7], v[162:165], v[192:195], v[4:7]
	v_mfma_f32_16x16x32_bf16 v[28:31], v[154:157], v[234:237], v[28:31]
	v_mfma_f32_16x16x32_bf16 v[0:3], v[162:165], v[234:237], v[0:3]
	v_mfma_f32_16x16x32_bf16 v[44:47], v[158:161], v[174:177], v[44:47]
	v_mfma_f32_16x16x32_bf16 v[12:15], v[166:169], v[174:177], v[12:15]
	s_mov_b32 m0, s37
	s_nop 0
	global_load_lds_dwordx4 v[244:245], off
	v_mfma_f32_16x16x32_bf16 v[40:43], v[158:161], v[182:185], v[40:43]
	v_mfma_f32_16x16x32_bf16 v[8:11], v[166:169], v[182:185], v[8:11]
	v_mfma_f32_16x16x32_bf16 v[32:35], v[158:161], v[230:233], v[32:35]
	v_mfma_f32_16x16x32_bf16 v[4:7], v[166:169], v[230:233], v[4:7]
	v_mfma_f32_16x16x32_bf16 v[28:31], v[158:161], v[238:241], v[28:31]
	v_mfma_f32_16x16x32_bf16 v[0:3], v[166:169], v[238:241], v[0:3]
	s_setprio 0
	s_barrier
	v_add_u32_e32 v150, 0x18000, v140
	v_add_u32_e32 v166, 0x1c000, v140
	ds_read_b128 v[134:137], v150
	ds_read_b128 v[142:145], v150 offset:1024
	ds_read_b128 v[146:149], v150 offset:2048
	ds_read_b128 v[150:153], v150 offset:3072
	ds_read_b128 v[154:157], v166
	ds_read_b128 v[158:161], v166 offset:1024
	ds_read_b128 v[162:165], v166 offset:2048
	ds_read_b128 v[166:169], v166 offset:3072
	ds_read_b128 v[170:173], v141 offset:32768
	ds_read_b128 v[174:177], v141 offset:33792
	ds_read_b128 v[178:181], v141 offset:34816
	ds_read_b128 v[182:185], v141 offset:35840
	ds_read_b128 v[192:195], v141 offset:36864
	ds_read_b128 v[230:233], v141 offset:37888
	ds_read_b128 v[234:237], v141 offset:38912
	ds_read_b128 v[238:241], v141 offset:39936
	s_add_i32 s68, 0, 0x18000
	s_add_i32 s69, 0, 0x1c000
	s_add_u32 s22, s28, 0xb0000
	s_addc_u32 s23, s29, 0
	s_mov_b32 m0, s44
	v_lshl_add_u64 v[246:247], s[22:23], 0, v[188:189]
	global_load_lds_dwordx4 v[246:247], off
	s_mov_b32 m0, s45
	v_lshl_add_u64 v[246:247], s[22:23], 0, v[128:129]
	global_load_lds_dwordx4 v[246:247], off
	s_waitcnt vmcnt(8)
	s_waitcnt lgkmcnt(0)
	s_barrier
; #define PG8_STAGE(bufoff, gbase, voff) do { _Pragma("unroll") for (int _i = 0; _i < 2; ++_i) \
;         __builtin_amdgcn_global_load_lds((const unsigned*)((const char*)(gbase) + (voff)[_i]), (PG8_LAS unsigned*)(lds + (bufoff) + ldsw + _i * 8192), 16, 0, 0); } while (0)
; #define PG8_LDA(dst, b, h) do { _Pragma("unroll") for (int m = 0; m < 4; ++m) _Pragma("unroll") for (int k = 0; k < 2; ++k) dst[m][k] = *(const PG8_LAS bf16x8*)(lds + PG8_SA(b, h) + aoff + m * 2048 + k * 1024); } while (0)
; #define PG8_MMA(ai, bj, At, Bt) do { __builtin_amdgcn_s_setprio(1); _Pragma("unroll") for (int m = 0; m < 4; ++m) _Pragma("unroll") for (int n = 0; n < 2; ++n) _Pragma("unroll") for (int k = 0; k < 2; ++k) \
;         acc[ai][bj][m][n] = __builtin_amdgcn_mfma_f32_16x16x32_bf16(Bt[n][k], At[m][k], acc[ai][bj][m][n], 0, 0, 0); __builtin_amdgcn_s_setprio(0); } while (0)
; #define PG8_WAIT_V(n) asm volatile("s_waitcnt vmcnt(" #n ")" ::: "memory")
; #define PG8_WAIT_L(n) asm volatile("s_waitcnt lgkmcnt(" #n ")" ::: "memory")
; #define PG8_BAR __builtin_amdgcn_s_barrier()
; #define PG8_SCHED __builtin_amdgcn_sched_barrier(0)
; template <class Epi, class Sched, bool ALIGN_EPI = false, bool SP2 = false>
; __device__ __forceinline__ void gemm_phase(PG8_LAS unsigned char* lds, const Gemm g, const Sched& S, const Epi& E) {
;     ...
;         for (int t = 0; t < nt; t += 2) {
;     ...
;             PG8_WAIT_V(8); PG8_WAIT_L(0); PG8_BAR; PG8_MMA(0, 0, At, B0); PG8_MMA(0, 1, At, B1); PG8_BAR; PG8_SCHED;
;             PG8_LDA(At, 1, 1); PG8_STAGE(PG8_SB(1, 0), b3, voffB); PG8_STAGE(PG8_SB(1, 1), b3 + hstepB, voffB); PG8_STAGE(PG8_SA(1, 0), a3, voffA);
;             PG8_WAIT_V(8); PG8_WAIT_L(0); PG8_BAR; PG8_MMA(1, 0, At, B0); PG8_MMA(1, 1, At, B1); PG8_BAR; PG8_SCHED;
	s_setprio 1
	s_waitcnt lgkmcnt(0)
	v_mfma_f32_16x16x32_bf16 v[124:127], v[134:137], v[170:173], v[124:127]
	v_mfma_f32_16x16x32_bf16 v[96:99], v[146:149], v[170:173], v[96:99]
	v_mfma_f32_16x16x32_bf16 v[120:123], v[134:137], v[178:181], v[120:123]
	v_mfma_f32_16x16x32_bf16 v[92:95], v[146:149], v[178:181], v[92:95]
	v_mfma_f32_16x16x32_bf16 v[116:119], v[134:137], v[192:195], v[116:119]
	v_mfma_f32_16x16x32_bf16 v[84:87], v[146:149], v[192:195], v[84:87]
	v_mfma_f32_16x16x32_bf16 v[112:115], v[134:137], v[234:237], v[112:115]
	v_mfma_f32_16x16x32_bf16 v[80:83], v[146:149], v[234:237], v[80:83]
	v_mfma_f32_16x16x32_bf16 v[124:127], v[142:145], v[174:177], v[124:127]
	v_mfma_f32_16x16x32_bf16 v[96:99], v[150:153], v[174:177], v[96:99]
	v_mfma_f32_16x16x32_bf16 v[120:123], v[142:145], v[182:185], v[120:123]
	v_mfma_f32_16x16x32_bf16 v[92:95], v[150:153], v[182:185], v[92:95]
	v_mfma_f32_16x16x32_bf16 v[116:119], v[142:145], v[230:233], v[116:119]
	v_mfma_f32_16x16x32_bf16 v[84:87], v[150:153], v[230:233], v[84:87]
	v_mfma_f32_16x16x32_bf16 v[112:115], v[142:145], v[238:241], v[112:115]
	v_mfma_f32_16x16x32_bf16 v[80:83], v[150:153], v[238:241], v[80:83]
	s_setprio 0
	s_setprio 1
	v_mfma_f32_16x16x32_bf16 v[64:67], v[154:157], v[170:173], v[64:67]
	v_mfma_f32_16x16x32_bf16 v[36:39], v[162:165], v[170:173], v[36:39]
	v_mfma_f32_16x16x32_bf16 v[56:59], v[154:157], v[178:181], v[56:59]
	v_mfma_f32_16x16x32_bf16 v[24:27], v[162:165], v[178:181], v[24:27]
	v_mfma_f32_16x16x32_bf16 v[52:55], v[154:157], v[192:195], v[52:55]
	v_mfma_f32_16x16x32_bf16 v[20:23], v[162:165], v[192:195], v[20:23]
	v_mfma_f32_16x16x32_bf16 v[48:51], v[154:157], v[234:237], v[48:51]
	v_mfma_f32_16x16x32_bf16 v[16:19], v[162:165], v[234:237], v[16:19]
	v_mfma_f32_16x16x32_bf16 v[64:67], v[158:161], v[174:177], v[64:67]
	v_mfma_f32_16x16x32_bf16 v[36:39], v[166:169], v[174:177], v[36:39]
	v_mfma_f32_16x16x32_bf16 v[56:59], v[158:161], v[182:185], v[56:59]
	v_mfma_f32_16x16x32_bf16 v[24:27], v[166:169], v[182:185], v[24:27]
	v_mfma_f32_16x16x32_bf16 v[52:55], v[158:161], v[230:233], v[52:55]
	v_mfma_f32_16x16x32_bf16 v[20:23], v[166:169], v[230:233], v[20:23]
	v_mfma_f32_16x16x32_bf16 v[48:51], v[158:161], v[238:241], v[48:51]
	v_mfma_f32_16x16x32_bf16 v[16:19], v[166:169], v[238:241], v[16:19]
	s_setprio 0
	s_barrier
	ds_read_b128 v[170:173], v141 offset:49152
	ds_read_b128 v[174:177], v141 offset:50176
	ds_read_b128 v[178:181], v141 offset:51200
	ds_read_b128 v[182:185], v141 offset:52224
	ds_read_b128 v[192:195], v141 offset:53248
	ds_read_b128 v[230:233], v141 offset:54272
	ds_read_b128 v[234:237], v141 offset:55296
	ds_read_b128 v[238:241], v141 offset:56320
	s_add_i32 s22, s68, s35
	s_mov_b32 m0, s22
	v_lshl_add_u64 v[186:187], v[186:187], 0, s[94:95]
	global_load_lds_dwordx4 v[186:187], off
	s_add_i32 m0, s22, 0x2000
	s_add_u32 s22, s26, 0xb0080
	v_lshl_add_u64 v[186:187], v[196:197], 0, s[94:95]
	s_addc_u32 s23, s27, 0
	s_add_i32 s26, s69, s35
	global_load_lds_dwordx4 v[186:187], off
	s_waitcnt vmcnt(4)
	s_waitcnt lgkmcnt(0)
	s_barrier
	s_setprio 1
	s_waitcnt lgkmcnt(0)
	v_mfma_f32_16x16x32_bf16 v[108:111], v[134:137], v[170:173], v[108:111]
	v_mfma_f32_16x16x32_bf16 v[76:79], v[146:149], v[170:173], v[76:79]
	s_mov_b32 m0, s26
	v_lshl_add_u64 v[186:187], s[22:23], 0, v[188:189]
	global_load_lds_dwordx4 v[186:187], off
	v_mfma_f32_16x16x32_bf16 v[104:107], v[134:137], v[178:181], v[104:107]
	v_mfma_f32_16x16x32_bf16 v[72:75], v[146:149], v[178:181], v[72:75]
	v_mfma_f32_16x16x32_bf16 v[100:103], v[134:137], v[192:195], v[100:103]
	v_mfma_f32_16x16x32_bf16 v[68:71], v[146:149], v[192:195], v[68:71]
	v_mfma_f32_16x16x32_bf16 v[88:91], v[134:137], v[234:237], v[88:91]
	v_mfma_f32_16x16x32_bf16 v[60:63], v[146:149], v[234:237], v[60:63]
	v_mfma_f32_16x16x32_bf16 v[108:111], v[142:145], v[174:177], v[108:111]
	v_mfma_f32_16x16x32_bf16 v[76:79], v[150:153], v[174:177], v[76:79]
	s_add_i32 m0, s26, 0x2000
	v_lshl_add_u64 v[186:187], s[22:23], 0, v[128:129]
	global_load_lds_dwordx4 v[186:187], off
	v_mfma_f32_16x16x32_bf16 v[104:107], v[142:145], v[182:185], v[104:107]
	v_mfma_f32_16x16x32_bf16 v[72:75], v[150:153], v[182:185], v[72:75]
	v_mfma_f32_16x16x32_bf16 v[100:103], v[142:145], v[230:233], v[100:103]
	v_mfma_f32_16x16x32_bf16 v[68:71], v[150:153], v[230:233], v[68:71]
	v_mfma_f32_16x16x32_bf16 v[88:91], v[142:145], v[238:241], v[88:91]
	v_mfma_f32_16x16x32_bf16 v[60:63], v[150:153], v[238:241], v[60:63]
	s_setprio 0
	s_setprio 1
	v_mfma_f32_16x16x32_bf16 v[44:47], v[154:157], v[170:173], v[44:47]
	v_mfma_f32_16x16x32_bf16 v[12:15], v[162:165], v[170:173], v[12:15]
	s_mov_b32 m0, s57
	v_lshl_add_u64 v[186:187], v[242:243], 0, s[94:95]
	global_load_lds_dwordx4 v[186:187], off
	v_mfma_f32_16x16x32_bf16 v[40:43], v[154:157], v[178:181], v[40:43]
	v_mfma_f32_16x16x32_bf16 v[8:11], v[162:165], v[178:181], v[8:11]
	v_mfma_f32_16x16x32_bf16 v[32:35], v[154:157], v[192:195], v[32:35]
	v_mfma_f32_16x16x32_bf16 v[4:7], v[162:165], v[192:195], v[4:7]
	v_mfma_f32_16x16x32_bf16 v[28:31], v[154:157], v[234:237], v[28:31]
	v_mfma_f32_16x16x32_bf16 v[0:3], v[162:165], v[234:237], v[0:3]
	v_mfma_f32_16x16x32_bf16 v[44:47], v[158:161], v[174:177], v[44:47]
	v_mfma_f32_16x16x32_bf16 v[12:15], v[166:169], v[174:177], v[12:15]
	s_mov_b32 m0, s58
	v_lshl_add_u64 v[186:187], v[244:245], 0, s[94:95]
	global_load_lds_dwordx4 v[186:187], off
	v_mfma_f32_16x16x32_bf16 v[40:43], v[158:161], v[182:185], v[40:43]
	v_mfma_f32_16x16x32_bf16 v[8:11], v[166:169], v[182:185], v[8:11]
	v_mfma_f32_16x16x32_bf16 v[32:35], v[158:161], v[230:233], v[32:35]
	v_mfma_f32_16x16x32_bf16 v[4:7], v[166:169], v[230:233], v[4:7]
	v_mfma_f32_16x16x32_bf16 v[28:31], v[158:161], v[238:241], v[28:31]
	v_mfma_f32_16x16x32_bf16 v[0:3], v[166:169], v[238:241], v[0:3]
	s_setprio 0
	s_barrier
	s_add_i32 s67, s67, 2
	s_add_u32 s65, s65, 0x100
	s_addc_u32 s66, s66, 0
	s_cmp_gt_u32 s67, 41
	s_mov_b64 s[22:23], s[24:25]
	s_cbranch_scc0 .LBB0_1993
	s_and_b64 vcc, exec, s[14:15]
	s_cbranch_vccz .LBB0_1996
	s_barrier
